# GEMM K loops: m0-to-DMA wait state filled by the segment's own ds_read instead of s_nop; mid-cluster setprio 0/1 pairs dropped
# speedup vs baseline: 1.0004x; 1.0004x over previous
.LBB0_163:
	ds_read_b128 v[152:155], v149
	ds_read_b128 v[156:159], v149 offset:1024
	ds_read_b128 v[160:163], v149 offset:2048
	ds_read_b128 v[164:167], v149 offset:3072
	ds_read_b128 v[168:171], v150
	ds_read_b128 v[172:175], v150 offset:1024
	ds_read_b128 v[176:179], v150 offset:2048
	ds_read_b128 v[180:183], v150 offset:3072
	s_add_u32 s24, s22, 0xfff80080
	s_addc_u32 s25, s23, -1
	s_cmp_eq_u32 s58, 28
	s_cselect_b32 s27, s15, s25
	s_cselect_b32 s26, s54, s24
	s_cselect_b32 s25, s13, s57
	s_cselect_b32 s24, s55, s56
	s_add_u32 s98, s24, s6
	s_addc_u32 s99, s25, s7
	s_add_u32 s100, s26, s6
	s_addc_u32 s101, s27, s7
	s_add_i32 m0, s21, 0xc000
	ds_read_b128 v[184:187], v151
	ds_read_b128 v[188:191], v151 offset:1024
	ds_read_b128 v[192:195], v151 offset:2048
	ds_read_b128 v[196:199], v151 offset:3072
	ds_read_b128 v[200:203], v151 offset:4096
	ds_read_b128 v[204:207], v151 offset:5120
	ds_read_b128 v[208:211], v151 offset:6144
	global_load_lds_dwordx4 v136, s[22:23]
	s_add_i32 m0, s21, 0xe000
	ds_read_b128 v[212:215], v151 offset:7168
	global_load_lds_dwordx4 v138, s[22:23]
	s_waitcnt vmcnt(8)
	s_waitcnt lgkmcnt(0)
	s_barrier
	s_setprio 1
	s_waitcnt lgkmcnt(0)
	v_mfma_f32_16x16x32_bf16 v[124:127], v[152:155], v[184:187], v[124:127]
	v_mfma_f32_16x16x32_bf16 v[120:123], v[160:163], v[184:187], v[120:123]
	v_mfma_f32_16x16x32_bf16 v[116:119], v[152:155], v[192:195], v[116:119]
	v_mfma_f32_16x16x32_bf16 v[108:111], v[160:163], v[192:195], v[108:111]
	v_mfma_f32_16x16x32_bf16 v[100:103], v[152:155], v[200:203], v[100:103]
	v_mfma_f32_16x16x32_bf16 v[92:95], v[160:163], v[200:203], v[92:95]
	v_mfma_f32_16x16x32_bf16 v[84:87], v[152:155], v[208:211], v[84:87]
	v_mfma_f32_16x16x32_bf16 v[76:79], v[160:163], v[208:211], v[76:79]
	v_mfma_f32_16x16x32_bf16 v[124:127], v[156:159], v[188:191], v[124:127]
	v_mfma_f32_16x16x32_bf16 v[120:123], v[164:167], v[188:191], v[120:123]
	v_mfma_f32_16x16x32_bf16 v[116:119], v[156:159], v[196:199], v[116:119]
	v_mfma_f32_16x16x32_bf16 v[108:111], v[164:167], v[196:199], v[108:111]
	v_mfma_f32_16x16x32_bf16 v[100:103], v[156:159], v[204:207], v[100:103]
	v_mfma_f32_16x16x32_bf16 v[92:95], v[164:167], v[204:207], v[92:95]
	v_mfma_f32_16x16x32_bf16 v[84:87], v[156:159], v[212:215], v[84:87]
	v_mfma_f32_16x16x32_bf16 v[76:79], v[164:167], v[212:215], v[76:79]
	v_mfma_f32_16x16x32_bf16 v[112:115], v[168:171], v[184:187], v[112:115]
	v_mfma_f32_16x16x32_bf16 v[104:107], v[176:179], v[184:187], v[104:107]
	v_mfma_f32_16x16x32_bf16 v[96:99], v[168:171], v[192:195], v[96:99]
	v_mfma_f32_16x16x32_bf16 v[88:91], v[176:179], v[192:195], v[88:91]
	v_mfma_f32_16x16x32_bf16 v[80:83], v[168:171], v[200:203], v[80:83]
	v_mfma_f32_16x16x32_bf16 v[72:75], v[176:179], v[200:203], v[72:75]
	v_mfma_f32_16x16x32_bf16 v[68:71], v[168:171], v[208:211], v[68:71]
	v_mfma_f32_16x16x32_bf16 v[64:67], v[176:179], v[208:211], v[64:67]
	v_mfma_f32_16x16x32_bf16 v[112:115], v[172:175], v[188:191], v[112:115]
	v_mfma_f32_16x16x32_bf16 v[104:107], v[180:183], v[188:191], v[104:107]
	v_mfma_f32_16x16x32_bf16 v[96:99], v[172:175], v[196:199], v[96:99]
	v_mfma_f32_16x16x32_bf16 v[88:91], v[180:183], v[196:199], v[88:91]
	v_mfma_f32_16x16x32_bf16 v[80:83], v[172:175], v[204:207], v[80:83]
	v_mfma_f32_16x16x32_bf16 v[72:75], v[180:183], v[204:207], v[72:75]
	v_mfma_f32_16x16x32_bf16 v[68:71], v[172:175], v[212:215], v[68:71]
	v_mfma_f32_16x16x32_bf16 v[64:67], v[180:183], v[212:215], v[64:67]
	s_setprio 0
	s_barrier
	s_add_i32 s59, s43, s28
	s_mov_b32 m0, s59
	ds_read_b128 v[184:187], v151 offset:16384
	ds_read_b128 v[188:191], v151 offset:17408
	ds_read_b128 v[192:195], v151 offset:18432
	ds_read_b128 v[196:199], v151 offset:19456
	global_load_lds_dwordx4 v130, s[24:25]
	s_add_i32 m0, s59, 0x2000
	s_add_u32 s62, s24, 0x200000
	s_addc_u32 s63, s25, 0
	s_add_i32 s59, s48, s28
	global_load_lds_dwordx4 v134, s[24:25]
	s_mov_b32 m0, s59
	ds_read_b128 v[212:215], v151 offset:23552
	global_load_lds_dwordx4 v130, s[62:63]
	s_add_i32 m0, s59, 0x2000
	ds_read_b128 v[208:211], v151 offset:22528
	global_load_lds_dwordx4 v134, s[62:63]
	s_mov_b32 m0, s21
	ds_read_b128 v[204:207], v151 offset:21504
	global_load_lds_dwordx4 v128, s[26:27]
	s_mov_b32 m0, s31
	ds_read_b128 v[200:203], v151 offset:20480
	global_load_lds_dwordx4 v132, s[26:27]
	s_waitcnt vmcnt(8)
	s_waitcnt lgkmcnt(0)
	s_barrier
	s_setprio 1
	s_waitcnt lgkmcnt(0)
	v_mfma_f32_16x16x32_bf16 v[60:63], v[152:155], v[184:187], v[60:63]
	v_mfma_f32_16x16x32_bf16 v[56:59], v[160:163], v[184:187], v[56:59]
	v_mfma_f32_16x16x32_bf16 v[52:55], v[152:155], v[192:195], v[52:55]
	v_mfma_f32_16x16x32_bf16 v[44:47], v[160:163], v[192:195], v[44:47]
	v_mfma_f32_16x16x32_bf16 v[36:39], v[152:155], v[200:203], v[36:39]
	v_mfma_f32_16x16x32_bf16 v[28:31], v[160:163], v[200:203], v[28:31]
	v_mfma_f32_16x16x32_bf16 v[20:23], v[152:155], v[208:211], v[20:23]
	v_mfma_f32_16x16x32_bf16 v[12:15], v[160:163], v[208:211], v[12:15]
	v_mfma_f32_16x16x32_bf16 v[60:63], v[156:159], v[188:191], v[60:63]
	v_mfma_f32_16x16x32_bf16 v[56:59], v[164:167], v[188:191], v[56:59]
	v_mfma_f32_16x16x32_bf16 v[52:55], v[156:159], v[196:199], v[52:55]
	v_mfma_f32_16x16x32_bf16 v[44:47], v[164:167], v[196:199], v[44:47]
	v_mfma_f32_16x16x32_bf16 v[36:39], v[156:159], v[204:207], v[36:39]
	v_mfma_f32_16x16x32_bf16 v[28:31], v[164:167], v[204:207], v[28:31]
	v_mfma_f32_16x16x32_bf16 v[20:23], v[156:159], v[212:215], v[20:23]
	v_mfma_f32_16x16x32_bf16 v[12:15], v[164:167], v[212:215], v[12:15]
	v_mfma_f32_16x16x32_bf16 v[48:51], v[168:171], v[184:187], v[48:51]
	v_mfma_f32_16x16x32_bf16 v[40:43], v[176:179], v[184:187], v[40:43]
	v_mfma_f32_16x16x32_bf16 v[32:35], v[168:171], v[192:195], v[32:35]
	v_mfma_f32_16x16x32_bf16 v[24:27], v[176:179], v[192:195], v[24:27]
	v_mfma_f32_16x16x32_bf16 v[16:19], v[168:171], v[200:203], v[16:19]
	v_mfma_f32_16x16x32_bf16 v[8:11], v[176:179], v[200:203], v[8:11]
	v_mfma_f32_16x16x32_bf16 v[4:7], v[168:171], v[208:211], v[4:7]
	v_mfma_f32_16x16x32_bf16 v[0:3], v[176:179], v[208:211], v[0:3]
	v_mfma_f32_16x16x32_bf16 v[48:51], v[172:175], v[188:191], v[48:51]
	v_mfma_f32_16x16x32_bf16 v[40:43], v[180:183], v[188:191], v[40:43]
	v_mfma_f32_16x16x32_bf16 v[32:35], v[172:175], v[196:199], v[32:35]
	v_mfma_f32_16x16x32_bf16 v[24:27], v[180:183], v[196:199], v[24:27]
	v_mfma_f32_16x16x32_bf16 v[16:19], v[172:175], v[204:207], v[16:19]
	v_mfma_f32_16x16x32_bf16 v[8:11], v[180:183], v[204:207], v[8:11]
	v_mfma_f32_16x16x32_bf16 v[4:7], v[172:175], v[212:215], v[4:7]
	v_mfma_f32_16x16x32_bf16 v[0:3], v[180:183], v[212:215], v[0:3]
	s_setprio 0
	s_barrier
	s_add_i32 s59, 0, 0x18000
	s_add_i32 s62, 0, 0x1c000
	v_add_u32_e32 v164, s59, v146
	v_add_u32_e32 v180, s62, v146
	ds_read_b128 v[152:155], v164
	ds_read_b128 v[156:159], v164 offset:1024
	ds_read_b128 v[160:163], v164 offset:2048
	ds_read_b128 v[164:167], v164 offset:3072
	ds_read_b128 v[168:171], v180
	ds_read_b128 v[172:175], v180 offset:1024
	ds_read_b128 v[176:179], v180 offset:2048
	ds_read_b128 v[180:183], v180 offset:3072
	s_add_u32 s26, s26, 0x80000
	s_addc_u32 s27, s27, 0
	s_mov_b32 m0, s34
	ds_read_b128 v[184:187], v151 offset:32768
	ds_read_b128 v[188:191], v151 offset:33792
	ds_read_b128 v[192:195], v151 offset:34816
	ds_read_b128 v[196:199], v151 offset:35840
	ds_read_b128 v[200:203], v151 offset:36864
	ds_read_b128 v[204:207], v151 offset:37888
	ds_read_b128 v[208:211], v151 offset:38912
	global_load_lds_dwordx4 v128, s[26:27]
	s_mov_b32 m0, s35
	ds_read_b128 v[212:215], v151 offset:39936
	global_load_lds_dwordx4 v132, s[26:27]
	s_waitcnt vmcnt(8)
	s_waitcnt lgkmcnt(0)
	s_barrier
	s_setprio 1
	s_waitcnt lgkmcnt(0)
	v_mfma_f32_16x16x32_bf16 v[124:127], v[152:155], v[184:187], v[124:127]
	v_mfma_f32_16x16x32_bf16 v[120:123], v[160:163], v[184:187], v[120:123]
	v_mfma_f32_16x16x32_bf16 v[116:119], v[152:155], v[192:195], v[116:119]
	v_mfma_f32_16x16x32_bf16 v[108:111], v[160:163], v[192:195], v[108:111]
	v_mfma_f32_16x16x32_bf16 v[100:103], v[152:155], v[200:203], v[100:103]
	v_mfma_f32_16x16x32_bf16 v[92:95], v[160:163], v[200:203], v[92:95]
	v_mfma_f32_16x16x32_bf16 v[84:87], v[152:155], v[208:211], v[84:87]
	v_mfma_f32_16x16x32_bf16 v[76:79], v[160:163], v[208:211], v[76:79]
	v_mfma_f32_16x16x32_bf16 v[124:127], v[156:159], v[188:191], v[124:127]
	v_mfma_f32_16x16x32_bf16 v[120:123], v[164:167], v[188:191], v[120:123]
	v_mfma_f32_16x16x32_bf16 v[116:119], v[156:159], v[196:199], v[116:119]
	v_mfma_f32_16x16x32_bf16 v[108:111], v[164:167], v[196:199], v[108:111]
	v_mfma_f32_16x16x32_bf16 v[100:103], v[156:159], v[204:207], v[100:103]
	v_mfma_f32_16x16x32_bf16 v[92:95], v[164:167], v[204:207], v[92:95]
	v_mfma_f32_16x16x32_bf16 v[84:87], v[156:159], v[212:215], v[84:87]
	v_mfma_f32_16x16x32_bf16 v[76:79], v[164:167], v[212:215], v[76:79]
	v_mfma_f32_16x16x32_bf16 v[112:115], v[168:171], v[184:187], v[112:115]
	v_mfma_f32_16x16x32_bf16 v[104:107], v[176:179], v[184:187], v[104:107]
	v_mfma_f32_16x16x32_bf16 v[96:99], v[168:171], v[192:195], v[96:99]
	v_mfma_f32_16x16x32_bf16 v[88:91], v[176:179], v[192:195], v[88:91]
	v_mfma_f32_16x16x32_bf16 v[80:83], v[168:171], v[200:203], v[80:83]
	v_mfma_f32_16x16x32_bf16 v[72:75], v[176:179], v[200:203], v[72:75]
	v_mfma_f32_16x16x32_bf16 v[68:71], v[168:171], v[208:211], v[68:71]
	v_mfma_f32_16x16x32_bf16 v[64:67], v[176:179], v[208:211], v[64:67]
	v_mfma_f32_16x16x32_bf16 v[112:115], v[172:175], v[188:191], v[112:115]
	v_mfma_f32_16x16x32_bf16 v[104:107], v[180:183], v[188:191], v[104:107]
	v_mfma_f32_16x16x32_bf16 v[96:99], v[172:175], v[196:199], v[96:99]
	v_mfma_f32_16x16x32_bf16 v[88:91], v[180:183], v[196:199], v[88:91]
	v_mfma_f32_16x16x32_bf16 v[80:83], v[172:175], v[204:207], v[80:83]
	v_mfma_f32_16x16x32_bf16 v[72:75], v[180:183], v[204:207], v[72:75]
	v_mfma_f32_16x16x32_bf16 v[68:71], v[172:175], v[212:215], v[68:71]
	v_mfma_f32_16x16x32_bf16 v[64:67], v[180:183], v[212:215], v[64:67]
	s_setprio 0
	s_barrier
	s_add_i32 s26, s59, s28
	s_mov_b32 m0, s26
	ds_read_b128 v[184:187], v151 offset:49152
	ds_read_b128 v[188:191], v151 offset:50176
	ds_read_b128 v[192:195], v151 offset:51200
	ds_read_b128 v[196:199], v151 offset:52224
	global_load_lds_dwordx4 v130, s[98:99]
	s_add_i32 m0, s26, 0x2000
	s_add_u32 s24, s24, 0x200080
	s_addc_u32 s25, s25, 0
	s_add_i32 s26, s62, s28
	global_load_lds_dwordx4 v134, s[98:99]
	s_mov_b32 m0, s26
	ds_read_b128 v[212:215], v151 offset:56320
	global_load_lds_dwordx4 v130, s[24:25]
	s_add_i32 m0, s26, 0x2000
	ds_read_b128 v[208:211], v151 offset:55296
	global_load_lds_dwordx4 v134, s[24:25]
	s_mov_b32 m0, s37
	ds_read_b128 v[204:207], v151 offset:54272
	global_load_lds_dwordx4 v128, s[100:101]
	s_mov_b32 m0, s38
	ds_read_b128 v[200:203], v151 offset:53248
	global_load_lds_dwordx4 v132, s[100:101]
	s_waitcnt vmcnt(8)
	s_waitcnt lgkmcnt(0)
	s_barrier
	s_setprio 1
	s_waitcnt lgkmcnt(0)
	v_mfma_f32_16x16x32_bf16 v[60:63], v[152:155], v[184:187], v[60:63]
	v_mfma_f32_16x16x32_bf16 v[56:59], v[160:163], v[184:187], v[56:59]
	v_mfma_f32_16x16x32_bf16 v[52:55], v[152:155], v[192:195], v[52:55]
	v_mfma_f32_16x16x32_bf16 v[44:47], v[160:163], v[192:195], v[44:47]
	v_mfma_f32_16x16x32_bf16 v[36:39], v[152:155], v[200:203], v[36:39]
	v_mfma_f32_16x16x32_bf16 v[28:31], v[160:163], v[200:203], v[28:31]
	v_mfma_f32_16x16x32_bf16 v[20:23], v[152:155], v[208:211], v[20:23]
	v_mfma_f32_16x16x32_bf16 v[12:15], v[160:163], v[208:211], v[12:15]
	v_mfma_f32_16x16x32_bf16 v[60:63], v[156:159], v[188:191], v[60:63]
	v_mfma_f32_16x16x32_bf16 v[56:59], v[164:167], v[188:191], v[56:59]
	v_mfma_f32_16x16x32_bf16 v[52:55], v[156:159], v[196:199], v[52:55]
	v_mfma_f32_16x16x32_bf16 v[44:47], v[164:167], v[196:199], v[44:47]
	v_mfma_f32_16x16x32_bf16 v[36:39], v[156:159], v[204:207], v[36:39]
	v_mfma_f32_16x16x32_bf16 v[28:31], v[164:167], v[204:207], v[28:31]
	v_mfma_f32_16x16x32_bf16 v[20:23], v[156:159], v[212:215], v[20:23]
	v_mfma_f32_16x16x32_bf16 v[12:15], v[164:167], v[212:215], v[12:15]
	v_mfma_f32_16x16x32_bf16 v[48:51], v[168:171], v[184:187], v[48:51]
	v_mfma_f32_16x16x32_bf16 v[40:43], v[176:179], v[184:187], v[40:43]
	v_mfma_f32_16x16x32_bf16 v[32:35], v[168:171], v[192:195], v[32:35]
	v_mfma_f32_16x16x32_bf16 v[24:27], v[176:179], v[192:195], v[24:27]
	v_mfma_f32_16x16x32_bf16 v[16:19], v[168:171], v[200:203], v[16:19]
	v_mfma_f32_16x16x32_bf16 v[8:11], v[176:179], v[200:203], v[8:11]
	v_mfma_f32_16x16x32_bf16 v[4:7], v[168:171], v[208:211], v[4:7]
	v_mfma_f32_16x16x32_bf16 v[0:3], v[176:179], v[208:211], v[0:3]
	v_mfma_f32_16x16x32_bf16 v[48:51], v[172:175], v[188:191], v[48:51]
	v_mfma_f32_16x16x32_bf16 v[40:43], v[180:183], v[188:191], v[40:43]
	v_mfma_f32_16x16x32_bf16 v[32:35], v[172:175], v[196:199], v[32:35]
	v_mfma_f32_16x16x32_bf16 v[24:27], v[180:183], v[196:199], v[24:27]
	v_mfma_f32_16x16x32_bf16 v[16:19], v[172:175], v[204:207], v[16:19]
	v_mfma_f32_16x16x32_bf16 v[8:11], v[180:183], v[204:207], v[8:11]
	v_mfma_f32_16x16x32_bf16 v[4:7], v[172:175], v[212:215], v[4:7]
	v_mfma_f32_16x16x32_bf16 v[0:3], v[180:183], v[212:215], v[0:3]
	s_setprio 0
	s_barrier
	s_add_i32 s58, s58, 2
	s_add_u32 s22, s22, 0x100
	s_addc_u32 s23, s23, 0
	s_add_u32 s56, s56, 0x100
	s_addc_u32 s57, s57, 0
	s_cmp_gt_u32 s58, 29
	s_cbranch_scc0 .LBB0_163
	s_and_b64 vcc, exec, s[10:11]
	s_cbranch_vccz .LBB0_166
	s_barrier

.LBB0_188:
	ds_read_b128 v[154:157], v149
	ds_read_b128 v[158:161], v149 offset:1024
	ds_read_b128 v[162:165], v149 offset:2048
	ds_read_b128 v[166:169], v149 offset:3072
	ds_read_b128 v[170:173], v150
	ds_read_b128 v[174:177], v150 offset:1024
	ds_read_b128 v[178:181], v150 offset:2048
	ds_read_b128 v[182:185], v150 offset:3072
	s_add_u32 s34, s30, 0xfff00080
	s_addc_u32 s35, s31, -1
	s_cmp_eq_u32 s79, 60
	s_cselect_b32 s37, s23, s35
	s_cselect_b32 s36, s73, s34
	s_cselect_b32 s35, s21, s78
	s_cselect_b32 s34, s74, s75
	s_add_u32 s98, s34, s10
	s_addc_u32 s99, s35, s11
	s_add_u32 s100, s36, s10
	s_addc_u32 s101, s37, s11
	s_add_i32 m0, s49, 0xc000
	ds_read_b128 v[186:189], v151
	ds_read_b128 v[190:193], v151 offset:1024
	ds_read_b128 v[194:197], v151 offset:2048
	ds_read_b128 v[198:201], v151 offset:3072
	ds_read_b128 v[202:205], v151 offset:4096
	ds_read_b128 v[206:209], v151 offset:5120
	ds_read_b128 v[210:213], v151 offset:6144
	global_load_lds_dwordx4 v136, s[30:31]
	s_add_i32 m0, s49, 0xe000
	ds_read_b128 v[214:217], v151 offset:7168
	global_load_lds_dwordx4 v138, s[30:31]
	s_waitcnt vmcnt(8)
	s_waitcnt lgkmcnt(0)
	s_barrier
	s_setprio 1
	s_waitcnt lgkmcnt(0)
	v_mfma_f32_16x16x32_bf16 v[124:127], v[154:157], v[186:189], v[124:127]
	v_mfma_f32_16x16x32_bf16 v[120:123], v[162:165], v[186:189], v[120:123]
	v_mfma_f32_16x16x32_bf16 v[116:119], v[154:157], v[194:197], v[116:119]
	v_mfma_f32_16x16x32_bf16 v[112:115], v[162:165], v[194:197], v[112:115]
	v_mfma_f32_16x16x32_bf16 v[104:107], v[154:157], v[202:205], v[104:107]
	v_mfma_f32_16x16x32_bf16 v[96:99], v[162:165], v[202:205], v[96:99]
	v_mfma_f32_16x16x32_bf16 v[76:79], v[154:157], v[210:213], v[76:79]
	v_mfma_f32_16x16x32_bf16 v[72:75], v[162:165], v[210:213], v[72:75]
	v_mfma_f32_16x16x32_bf16 v[124:127], v[158:161], v[190:193], v[124:127]
	v_mfma_f32_16x16x32_bf16 v[120:123], v[166:169], v[190:193], v[120:123]
	v_mfma_f32_16x16x32_bf16 v[116:119], v[158:161], v[198:201], v[116:119]
	v_mfma_f32_16x16x32_bf16 v[112:115], v[166:169], v[198:201], v[112:115]
	v_mfma_f32_16x16x32_bf16 v[104:107], v[158:161], v[206:209], v[104:107]
	v_mfma_f32_16x16x32_bf16 v[96:99], v[166:169], v[206:209], v[96:99]
	v_mfma_f32_16x16x32_bf16 v[76:79], v[158:161], v[214:217], v[76:79]
	v_mfma_f32_16x16x32_bf16 v[72:75], v[166:169], v[214:217], v[72:75]
	v_mfma_f32_16x16x32_bf16 v[108:111], v[170:173], v[186:189], v[108:111]
	v_mfma_f32_16x16x32_bf16 v[100:103], v[178:181], v[186:189], v[100:103]
	v_mfma_f32_16x16x32_bf16 v[92:95], v[170:173], v[194:197], v[92:95]
	v_mfma_f32_16x16x32_bf16 v[88:91], v[178:181], v[194:197], v[88:91]
	v_mfma_f32_16x16x32_bf16 v[84:87], v[170:173], v[202:205], v[84:87]
	v_mfma_f32_16x16x32_bf16 v[80:83], v[178:181], v[202:205], v[80:83]
	v_mfma_f32_16x16x32_bf16 v[68:71], v[170:173], v[210:213], v[68:71]
	v_mfma_f32_16x16x32_bf16 v[64:67], v[178:181], v[210:213], v[64:67]
	v_mfma_f32_16x16x32_bf16 v[108:111], v[174:177], v[190:193], v[108:111]
	v_mfma_f32_16x16x32_bf16 v[100:103], v[182:185], v[190:193], v[100:103]
	v_mfma_f32_16x16x32_bf16 v[92:95], v[174:177], v[198:201], v[92:95]
	v_mfma_f32_16x16x32_bf16 v[88:91], v[182:185], v[198:201], v[88:91]
	v_mfma_f32_16x16x32_bf16 v[84:87], v[174:177], v[206:209], v[84:87]
	v_mfma_f32_16x16x32_bf16 v[80:83], v[182:185], v[206:209], v[80:83]
	v_mfma_f32_16x16x32_bf16 v[68:71], v[174:177], v[214:217], v[68:71]
	v_mfma_f32_16x16x32_bf16 v[64:67], v[182:185], v[214:217], v[64:67]
	s_setprio 0
	s_barrier
	s_add_i32 s80, s63, s38
	s_mov_b32 m0, s80
	ds_read_b128 v[186:189], v151 offset:16384
	ds_read_b128 v[190:193], v151 offset:17408
	ds_read_b128 v[194:197], v151 offset:18432
	ds_read_b128 v[198:201], v151 offset:19456
	global_load_lds_dwordx4 v130, s[34:35]
	s_add_i32 m0, s80, 0x2000
	s_add_u32 s80, s34, 0x100000
	s_addc_u32 s81, s35, 0
	s_add_i32 s82, s68, s38
	global_load_lds_dwordx4 v134, s[34:35]
	s_mov_b32 m0, s82
	ds_read_b128 v[214:217], v151 offset:23552
	global_load_lds_dwordx4 v130, s[80:81]
	s_add_i32 m0, s82, 0x2000
	ds_read_b128 v[210:213], v151 offset:22528
	global_load_lds_dwordx4 v134, s[80:81]
	s_mov_b32 m0, s49
	ds_read_b128 v[206:209], v151 offset:21504
	global_load_lds_dwordx4 v128, s[36:37]
	s_mov_b32 m0, s54
	ds_read_b128 v[202:205], v151 offset:20480
	global_load_lds_dwordx4 v132, s[36:37]
	s_waitcnt vmcnt(8)
	s_waitcnt lgkmcnt(0)
	s_barrier
	s_setprio 1
	s_waitcnt lgkmcnt(0)
	v_mfma_f32_16x16x32_bf16 v[60:63], v[154:157], v[186:189], v[60:63]
	v_mfma_f32_16x16x32_bf16 v[56:59], v[162:165], v[186:189], v[56:59]
	v_mfma_f32_16x16x32_bf16 v[44:47], v[154:157], v[194:197], v[44:47]
	v_mfma_f32_16x16x32_bf16 v[40:43], v[162:165], v[194:197], v[40:43]
	v_mfma_f32_16x16x32_bf16 v[28:31], v[154:157], v[202:205], v[28:31]
	v_mfma_f32_16x16x32_bf16 v[24:27], v[162:165], v[202:205], v[24:27]
	v_mfma_f32_16x16x32_bf16 v[12:15], v[154:157], v[210:213], v[12:15]
	v_mfma_f32_16x16x32_bf16 v[8:11], v[162:165], v[210:213], v[8:11]
	v_mfma_f32_16x16x32_bf16 v[60:63], v[158:161], v[190:193], v[60:63]
	v_mfma_f32_16x16x32_bf16 v[56:59], v[166:169], v[190:193], v[56:59]
	v_mfma_f32_16x16x32_bf16 v[44:47], v[158:161], v[198:201], v[44:47]
	v_mfma_f32_16x16x32_bf16 v[40:43], v[166:169], v[198:201], v[40:43]
	v_mfma_f32_16x16x32_bf16 v[28:31], v[158:161], v[206:209], v[28:31]
	v_mfma_f32_16x16x32_bf16 v[24:27], v[166:169], v[206:209], v[24:27]
	v_mfma_f32_16x16x32_bf16 v[12:15], v[158:161], v[214:217], v[12:15]
	v_mfma_f32_16x16x32_bf16 v[8:11], v[166:169], v[214:217], v[8:11]
	v_mfma_f32_16x16x32_bf16 v[52:55], v[170:173], v[186:189], v[52:55]
	v_mfma_f32_16x16x32_bf16 v[48:51], v[178:181], v[186:189], v[48:51]
	v_mfma_f32_16x16x32_bf16 v[36:39], v[170:173], v[194:197], v[36:39]
	v_mfma_f32_16x16x32_bf16 v[32:35], v[178:181], v[194:197], v[32:35]
	v_mfma_f32_16x16x32_bf16 v[20:23], v[170:173], v[202:205], v[20:23]
	v_mfma_f32_16x16x32_bf16 v[16:19], v[178:181], v[202:205], v[16:19]
	v_mfma_f32_16x16x32_bf16 v[4:7], v[170:173], v[210:213], v[4:7]
	v_mfma_f32_16x16x32_bf16 v[0:3], v[178:181], v[210:213], v[0:3]
	v_mfma_f32_16x16x32_bf16 v[52:55], v[174:177], v[190:193], v[52:55]
	v_mfma_f32_16x16x32_bf16 v[48:51], v[182:185], v[190:193], v[48:51]
	v_mfma_f32_16x16x32_bf16 v[36:39], v[174:177], v[198:201], v[36:39]
	v_mfma_f32_16x16x32_bf16 v[32:35], v[182:185], v[198:201], v[32:35]
	v_mfma_f32_16x16x32_bf16 v[20:23], v[174:177], v[206:209], v[20:23]
	v_mfma_f32_16x16x32_bf16 v[16:19], v[182:185], v[206:209], v[16:19]
	v_mfma_f32_16x16x32_bf16 v[4:7], v[174:177], v[214:217], v[4:7]
	v_mfma_f32_16x16x32_bf16 v[0:3], v[182:185], v[214:217], v[0:3]
	s_setprio 0
	s_barrier
	s_add_i32 s80, 0, 0x18000
	s_add_i32 s81, 0, 0x1c000
	v_add_u32_e32 v166, s80, v147
	v_add_u32_e32 v182, s81, v147
	ds_read_b128 v[154:157], v166
	ds_read_b128 v[158:161], v166 offset:1024
	ds_read_b128 v[162:165], v166 offset:2048
	ds_read_b128 v[166:169], v166 offset:3072
	ds_read_b128 v[170:173], v182
	ds_read_b128 v[174:177], v182 offset:1024
	ds_read_b128 v[178:181], v182 offset:2048
	ds_read_b128 v[182:185], v182 offset:3072
	s_add_u32 s36, s36, 0x100000
	s_addc_u32 s37, s37, 0
	s_mov_b32 m0, s55
	ds_read_b128 v[186:189], v151 offset:32768
	ds_read_b128 v[190:193], v151 offset:33792
	ds_read_b128 v[194:197], v151 offset:34816
	ds_read_b128 v[198:201], v151 offset:35840
	ds_read_b128 v[202:205], v151 offset:36864
	ds_read_b128 v[206:209], v151 offset:37888
	ds_read_b128 v[210:213], v151 offset:38912
	global_load_lds_dwordx4 v128, s[36:37]
	s_mov_b32 m0, s56
	ds_read_b128 v[214:217], v151 offset:39936
	global_load_lds_dwordx4 v132, s[36:37]
	s_waitcnt vmcnt(8)
	s_waitcnt lgkmcnt(0)
	s_barrier
	s_setprio 1
	s_waitcnt lgkmcnt(0)
	v_mfma_f32_16x16x32_bf16 v[124:127], v[154:157], v[186:189], v[124:127]
	v_mfma_f32_16x16x32_bf16 v[120:123], v[162:165], v[186:189], v[120:123]
	v_mfma_f32_16x16x32_bf16 v[116:119], v[154:157], v[194:197], v[116:119]
	v_mfma_f32_16x16x32_bf16 v[112:115], v[162:165], v[194:197], v[112:115]
	v_mfma_f32_16x16x32_bf16 v[104:107], v[154:157], v[202:205], v[104:107]
	v_mfma_f32_16x16x32_bf16 v[96:99], v[162:165], v[202:205], v[96:99]
	v_mfma_f32_16x16x32_bf16 v[76:79], v[154:157], v[210:213], v[76:79]
	v_mfma_f32_16x16x32_bf16 v[72:75], v[162:165], v[210:213], v[72:75]
	v_mfma_f32_16x16x32_bf16 v[124:127], v[158:161], v[190:193], v[124:127]
	v_mfma_f32_16x16x32_bf16 v[120:123], v[166:169], v[190:193], v[120:123]
	v_mfma_f32_16x16x32_bf16 v[116:119], v[158:161], v[198:201], v[116:119]
	v_mfma_f32_16x16x32_bf16 v[112:115], v[166:169], v[198:201], v[112:115]
	v_mfma_f32_16x16x32_bf16 v[104:107], v[158:161], v[206:209], v[104:107]
	v_mfma_f32_16x16x32_bf16 v[96:99], v[166:169], v[206:209], v[96:99]
	v_mfma_f32_16x16x32_bf16 v[76:79], v[158:161], v[214:217], v[76:79]
	v_mfma_f32_16x16x32_bf16 v[72:75], v[166:169], v[214:217], v[72:75]
	v_mfma_f32_16x16x32_bf16 v[108:111], v[170:173], v[186:189], v[108:111]
	v_mfma_f32_16x16x32_bf16 v[100:103], v[178:181], v[186:189], v[100:103]
	v_mfma_f32_16x16x32_bf16 v[92:95], v[170:173], v[194:197], v[92:95]
	v_mfma_f32_16x16x32_bf16 v[88:91], v[178:181], v[194:197], v[88:91]
	v_mfma_f32_16x16x32_bf16 v[84:87], v[170:173], v[202:205], v[84:87]
	v_mfma_f32_16x16x32_bf16 v[80:83], v[178:181], v[202:205], v[80:83]
	v_mfma_f32_16x16x32_bf16 v[68:71], v[170:173], v[210:213], v[68:71]
	v_mfma_f32_16x16x32_bf16 v[64:67], v[178:181], v[210:213], v[64:67]
	v_mfma_f32_16x16x32_bf16 v[108:111], v[174:177], v[190:193], v[108:111]
	v_mfma_f32_16x16x32_bf16 v[100:103], v[182:185], v[190:193], v[100:103]
	v_mfma_f32_16x16x32_bf16 v[92:95], v[174:177], v[198:201], v[92:95]
	v_mfma_f32_16x16x32_bf16 v[88:91], v[182:185], v[198:201], v[88:91]
	v_mfma_f32_16x16x32_bf16 v[84:87], v[174:177], v[206:209], v[84:87]
	v_mfma_f32_16x16x32_bf16 v[80:83], v[182:185], v[206:209], v[80:83]
	v_mfma_f32_16x16x32_bf16 v[68:71], v[174:177], v[214:217], v[68:71]
	v_mfma_f32_16x16x32_bf16 v[64:67], v[182:185], v[214:217], v[64:67]
	s_setprio 0
	s_barrier
	s_add_i32 s36, s80, s38
	s_mov_b32 m0, s36
	ds_read_b128 v[186:189], v151 offset:49152
	ds_read_b128 v[190:193], v151 offset:50176
	ds_read_b128 v[194:197], v151 offset:51200
	ds_read_b128 v[198:201], v151 offset:52224
	global_load_lds_dwordx4 v130, s[98:99]
	s_add_i32 m0, s36, 0x2000
	s_add_u32 s34, s34, 0x100080
	s_addc_u32 s35, s35, 0
	s_add_i32 s36, s81, s38
	global_load_lds_dwordx4 v134, s[98:99]
	s_mov_b32 m0, s36
	ds_read_b128 v[214:217], v151 offset:56320
	global_load_lds_dwordx4 v130, s[34:35]
	s_add_i32 m0, s36, 0x2000
	ds_read_b128 v[210:213], v151 offset:55296
	global_load_lds_dwordx4 v134, s[34:35]
	s_mov_b32 m0, s58
	ds_read_b128 v[206:209], v151 offset:54272
	global_load_lds_dwordx4 v128, s[100:101]
	s_mov_b32 m0, s59
	ds_read_b128 v[202:205], v151 offset:53248
	global_load_lds_dwordx4 v132, s[100:101]
	s_waitcnt vmcnt(8)
	s_waitcnt lgkmcnt(0)
	s_barrier
	s_setprio 1
	s_waitcnt lgkmcnt(0)
	v_mfma_f32_16x16x32_bf16 v[60:63], v[154:157], v[186:189], v[60:63]
	v_mfma_f32_16x16x32_bf16 v[56:59], v[162:165], v[186:189], v[56:59]
	v_mfma_f32_16x16x32_bf16 v[44:47], v[154:157], v[194:197], v[44:47]
	v_mfma_f32_16x16x32_bf16 v[40:43], v[162:165], v[194:197], v[40:43]
	v_mfma_f32_16x16x32_bf16 v[28:31], v[154:157], v[202:205], v[28:31]
	v_mfma_f32_16x16x32_bf16 v[24:27], v[162:165], v[202:205], v[24:27]
	v_mfma_f32_16x16x32_bf16 v[12:15], v[154:157], v[210:213], v[12:15]
	v_mfma_f32_16x16x32_bf16 v[8:11], v[162:165], v[210:213], v[8:11]
	v_mfma_f32_16x16x32_bf16 v[60:63], v[158:161], v[190:193], v[60:63]
	v_mfma_f32_16x16x32_bf16 v[56:59], v[166:169], v[190:193], v[56:59]
	v_mfma_f32_16x16x32_bf16 v[44:47], v[158:161], v[198:201], v[44:47]
	v_mfma_f32_16x16x32_bf16 v[40:43], v[166:169], v[198:201], v[40:43]
	v_mfma_f32_16x16x32_bf16 v[28:31], v[158:161], v[206:209], v[28:31]
	v_mfma_f32_16x16x32_bf16 v[24:27], v[166:169], v[206:209], v[24:27]
	v_mfma_f32_16x16x32_bf16 v[12:15], v[158:161], v[214:217], v[12:15]
	v_mfma_f32_16x16x32_bf16 v[8:11], v[166:169], v[214:217], v[8:11]
	v_mfma_f32_16x16x32_bf16 v[52:55], v[170:173], v[186:189], v[52:55]
	v_mfma_f32_16x16x32_bf16 v[48:51], v[178:181], v[186:189], v[48:51]
	v_mfma_f32_16x16x32_bf16 v[36:39], v[170:173], v[194:197], v[36:39]
	v_mfma_f32_16x16x32_bf16 v[32:35], v[178:181], v[194:197], v[32:35]
	v_mfma_f32_16x16x32_bf16 v[20:23], v[170:173], v[202:205], v[20:23]
	v_mfma_f32_16x16x32_bf16 v[16:19], v[178:181], v[202:205], v[16:19]
	v_mfma_f32_16x16x32_bf16 v[4:7], v[170:173], v[210:213], v[4:7]
	v_mfma_f32_16x16x32_bf16 v[0:3], v[178:181], v[210:213], v[0:3]
	v_mfma_f32_16x16x32_bf16 v[52:55], v[174:177], v[190:193], v[52:55]
	v_mfma_f32_16x16x32_bf16 v[48:51], v[182:185], v[190:193], v[48:51]
	v_mfma_f32_16x16x32_bf16 v[36:39], v[174:177], v[198:201], v[36:39]
	v_mfma_f32_16x16x32_bf16 v[32:35], v[182:185], v[198:201], v[32:35]
	v_mfma_f32_16x16x32_bf16 v[20:23], v[174:177], v[206:209], v[20:23]
	v_mfma_f32_16x16x32_bf16 v[16:19], v[182:185], v[206:209], v[16:19]
	v_mfma_f32_16x16x32_bf16 v[4:7], v[174:177], v[214:217], v[4:7]
	v_mfma_f32_16x16x32_bf16 v[0:3], v[182:185], v[214:217], v[0:3]
	s_setprio 0
	s_barrier
	s_add_i32 s79, s79, 2
	s_add_u32 s30, s30, 0x100
	s_addc_u32 s31, s31, 0
	s_add_u32 s75, s75, 0x100
	s_addc_u32 s78, s78, 0
	s_cmp_gt_u32 s79, 61
	s_cbranch_scc0 .LBB0_188
	s_and_b64 vcc, exec, s[12:13]
	s_cbranch_vccz .LBB0_191
	s_barrier

.LBB0_431:
	ds_read_b128 v[128:131], v207
	ds_read_b128 v[132:135], v207 offset:1024
	ds_read_b128 v[136:139], v207 offset:2048
	ds_read_b128 v[140:143], v207 offset:3072
	ds_read_b128 v[144:147], v208
	ds_read_b128 v[148:151], v208 offset:1024
	ds_read_b128 v[152:155], v208 offset:2048
	ds_read_b128 v[156:159], v208 offset:3072
	s_add_u32 s28, s26, 0xfff00080
	s_addc_u32 s29, s27, -1
	s_cmp_eq_u32 s55, 60
	s_cselect_b32 s31, s15, s29
	s_cselect_b32 s30, s21, s28
	s_cselect_b32 s29, s13, s54
	s_cselect_b32 s28, s52, s53
	s_add_u32 s98, s28, s8
	s_addc_u32 s99, s29, s9
	s_add_u32 s100, s30, s8
	s_addc_u32 s101, s31, s9
	s_add_i32 m0, s23, 0xc000
	ds_read_b128 v[160:163], v209
	ds_read_b128 v[164:167], v209 offset:1024
	ds_read_b128 v[168:171], v209 offset:2048
	ds_read_b128 v[172:175], v209 offset:3072
	ds_read_b128 v[192:195], v209 offset:4096
	ds_read_b128 v[196:199], v209 offset:5120
	ds_read_b128 v[200:203], v209 offset:6144
	global_load_lds_dwordx4 v184, s[26:27]
	s_add_i32 m0, s23, 0xe000
	ds_read_b128 v[212:215], v209 offset:7168
	global_load_lds_dwordx4 v186, s[26:27]
	s_waitcnt vmcnt(8)
	s_waitcnt lgkmcnt(0)
	s_barrier
	s_setprio 1
	s_waitcnt lgkmcnt(0)
	v_mfma_f32_16x16x32_bf16 v[124:127], v[128:131], v[160:163], v[124:127]
	v_mfma_f32_16x16x32_bf16 v[120:123], v[136:139], v[160:163], v[120:123]
	v_mfma_f32_16x16x32_bf16 v[108:111], v[128:131], v[168:171], v[108:111]
	v_mfma_f32_16x16x32_bf16 v[104:107], v[136:139], v[168:171], v[104:107]
	v_mfma_f32_16x16x32_bf16 v[92:95], v[128:131], v[192:195], v[92:95]
	v_mfma_f32_16x16x32_bf16 v[88:91], v[136:139], v[192:195], v[88:91]
	v_mfma_f32_16x16x32_bf16 v[76:79], v[128:131], v[200:203], v[76:79]
	v_mfma_f32_16x16x32_bf16 v[72:75], v[136:139], v[200:203], v[72:75]
	v_mfma_f32_16x16x32_bf16 v[124:127], v[132:135], v[164:167], v[124:127]
	v_mfma_f32_16x16x32_bf16 v[120:123], v[140:143], v[164:167], v[120:123]
	v_mfma_f32_16x16x32_bf16 v[108:111], v[132:135], v[172:175], v[108:111]
	v_mfma_f32_16x16x32_bf16 v[104:107], v[140:143], v[172:175], v[104:107]
	v_mfma_f32_16x16x32_bf16 v[92:95], v[132:135], v[196:199], v[92:95]
	v_mfma_f32_16x16x32_bf16 v[88:91], v[140:143], v[196:199], v[88:91]
	v_mfma_f32_16x16x32_bf16 v[76:79], v[132:135], v[212:215], v[76:79]
	v_mfma_f32_16x16x32_bf16 v[72:75], v[140:143], v[212:215], v[72:75]
	v_mfma_f32_16x16x32_bf16 v[116:119], v[144:147], v[160:163], v[116:119]
	v_mfma_f32_16x16x32_bf16 v[112:115], v[152:155], v[160:163], v[112:115]
	v_mfma_f32_16x16x32_bf16 v[100:103], v[144:147], v[168:171], v[100:103]
	v_mfma_f32_16x16x32_bf16 v[96:99], v[152:155], v[168:171], v[96:99]
	v_mfma_f32_16x16x32_bf16 v[84:87], v[144:147], v[192:195], v[84:87]
	v_mfma_f32_16x16x32_bf16 v[80:83], v[152:155], v[192:195], v[80:83]
	v_mfma_f32_16x16x32_bf16 v[68:71], v[144:147], v[200:203], v[68:71]
	v_mfma_f32_16x16x32_bf16 v[64:67], v[152:155], v[200:203], v[64:67]
	v_mfma_f32_16x16x32_bf16 v[116:119], v[148:151], v[164:167], v[116:119]
	v_mfma_f32_16x16x32_bf16 v[112:115], v[156:159], v[164:167], v[112:115]
	v_mfma_f32_16x16x32_bf16 v[100:103], v[148:151], v[172:175], v[100:103]
	v_mfma_f32_16x16x32_bf16 v[96:99], v[156:159], v[172:175], v[96:99]
	v_mfma_f32_16x16x32_bf16 v[84:87], v[148:151], v[196:199], v[84:87]
	v_mfma_f32_16x16x32_bf16 v[80:83], v[156:159], v[196:199], v[80:83]
	v_mfma_f32_16x16x32_bf16 v[68:71], v[148:151], v[212:215], v[68:71]
	v_mfma_f32_16x16x32_bf16 v[64:67], v[156:159], v[212:215], v[64:67]
	s_setprio 0
	s_barrier
	s_add_i32 s58, s50, s3
	s_mov_b32 m0, s58
	ds_read_b128 v[160:163], v209 offset:16384
	ds_read_b128 v[164:167], v209 offset:17408
	ds_read_b128 v[168:171], v209 offset:18432
	ds_read_b128 v[172:175], v209 offset:19456
	global_load_lds_dwordx4 v178, s[28:29]
	s_add_i32 m0, s58, 0x2000
	s_add_u32 s58, s28, 0x100000
	s_addc_u32 s59, s29, 0
	s_add_i32 s62, s51, s3
	global_load_lds_dwordx4 v182, s[28:29]
	s_mov_b32 m0, s62
	ds_read_b128 v[212:215], v209 offset:23552
	global_load_lds_dwordx4 v178, s[58:59]
	s_add_i32 m0, s62, 0x2000
	ds_read_b128 v[200:203], v209 offset:22528
	global_load_lds_dwordx4 v182, s[58:59]
	s_mov_b32 m0, s23
	ds_read_b128 v[196:199], v209 offset:21504
	global_load_lds_dwordx4 v176, s[30:31]
	s_mov_b32 m0, s34
	ds_read_b128 v[192:195], v209 offset:20480
	global_load_lds_dwordx4 v180, s[30:31]
	s_waitcnt vmcnt(8)
	s_waitcnt lgkmcnt(0)
	s_barrier
	s_setprio 1
	s_waitcnt lgkmcnt(0)
	v_mfma_f32_16x16x32_bf16 v[60:63], v[128:131], v[160:163], v[60:63]
	v_mfma_f32_16x16x32_bf16 v[56:59], v[136:139], v[160:163], v[56:59]
	v_mfma_f32_16x16x32_bf16 v[44:47], v[128:131], v[168:171], v[44:47]
	v_mfma_f32_16x16x32_bf16 v[40:43], v[136:139], v[168:171], v[40:43]
	v_mfma_f32_16x16x32_bf16 v[28:31], v[128:131], v[192:195], v[28:31]
	v_mfma_f32_16x16x32_bf16 v[24:27], v[136:139], v[192:195], v[24:27]
	v_mfma_f32_16x16x32_bf16 v[12:15], v[128:131], v[200:203], v[12:15]
	v_mfma_f32_16x16x32_bf16 v[8:11], v[136:139], v[200:203], v[8:11]
	v_mfma_f32_16x16x32_bf16 v[60:63], v[132:135], v[164:167], v[60:63]
	v_mfma_f32_16x16x32_bf16 v[56:59], v[140:143], v[164:167], v[56:59]
	v_mfma_f32_16x16x32_bf16 v[44:47], v[132:135], v[172:175], v[44:47]
	v_mfma_f32_16x16x32_bf16 v[40:43], v[140:143], v[172:175], v[40:43]
	v_mfma_f32_16x16x32_bf16 v[28:31], v[132:135], v[196:199], v[28:31]
	v_mfma_f32_16x16x32_bf16 v[24:27], v[140:143], v[196:199], v[24:27]
	v_mfma_f32_16x16x32_bf16 v[12:15], v[132:135], v[212:215], v[12:15]
	v_mfma_f32_16x16x32_bf16 v[8:11], v[140:143], v[212:215], v[8:11]
	v_mfma_f32_16x16x32_bf16 v[52:55], v[144:147], v[160:163], v[52:55]
	v_mfma_f32_16x16x32_bf16 v[48:51], v[152:155], v[160:163], v[48:51]
	v_mfma_f32_16x16x32_bf16 v[36:39], v[144:147], v[168:171], v[36:39]
	v_mfma_f32_16x16x32_bf16 v[32:35], v[152:155], v[168:171], v[32:35]
	v_mfma_f32_16x16x32_bf16 v[20:23], v[144:147], v[192:195], v[20:23]
	v_mfma_f32_16x16x32_bf16 v[16:19], v[152:155], v[192:195], v[16:19]
	v_mfma_f32_16x16x32_bf16 v[4:7], v[144:147], v[200:203], v[4:7]
	v_mfma_f32_16x16x32_bf16 v[0:3], v[152:155], v[200:203], v[0:3]
	v_mfma_f32_16x16x32_bf16 v[52:55], v[148:151], v[164:167], v[52:55]
	v_mfma_f32_16x16x32_bf16 v[48:51], v[156:159], v[164:167], v[48:51]
	v_mfma_f32_16x16x32_bf16 v[36:39], v[148:151], v[172:175], v[36:39]
	v_mfma_f32_16x16x32_bf16 v[32:35], v[156:159], v[172:175], v[32:35]
	v_mfma_f32_16x16x32_bf16 v[20:23], v[148:151], v[196:199], v[20:23]
	v_mfma_f32_16x16x32_bf16 v[16:19], v[156:159], v[196:199], v[16:19]
	v_mfma_f32_16x16x32_bf16 v[4:7], v[148:151], v[212:215], v[4:7]
	v_mfma_f32_16x16x32_bf16 v[0:3], v[156:159], v[212:215], v[0:3]
	s_setprio 0
	s_barrier
	s_add_i32 s58, 0, 0x18000
	s_add_i32 s59, 0, 0x1c000
	v_add_u32_e32 v140, s58, v205
	v_add_u32_e32 v156, s59, v205
	ds_read_b128 v[128:131], v140
	ds_read_b128 v[132:135], v140 offset:1024
	ds_read_b128 v[136:139], v140 offset:2048
	ds_read_b128 v[140:143], v140 offset:3072
	ds_read_b128 v[144:147], v156
	ds_read_b128 v[148:151], v156 offset:1024
	ds_read_b128 v[152:155], v156 offset:2048
	ds_read_b128 v[156:159], v156 offset:3072
	s_add_u32 s30, s30, 0x100000
	s_addc_u32 s31, s31, 0
	s_mov_b32 m0, s35
	ds_read_b128 v[160:163], v209 offset:32768
	ds_read_b128 v[164:167], v209 offset:33792
	ds_read_b128 v[168:171], v209 offset:34816
	ds_read_b128 v[172:175], v209 offset:35840
	ds_read_b128 v[192:195], v209 offset:36864
	ds_read_b128 v[196:199], v209 offset:37888
	ds_read_b128 v[200:203], v209 offset:38912
	global_load_lds_dwordx4 v176, s[30:31]
	s_mov_b32 m0, s36
	ds_read_b128 v[212:215], v209 offset:39936
	global_load_lds_dwordx4 v180, s[30:31]
	s_waitcnt vmcnt(8)
	s_waitcnt lgkmcnt(0)
	s_barrier
	s_setprio 1
	s_waitcnt lgkmcnt(0)
	v_mfma_f32_16x16x32_bf16 v[124:127], v[128:131], v[160:163], v[124:127]
	v_mfma_f32_16x16x32_bf16 v[120:123], v[136:139], v[160:163], v[120:123]
	v_mfma_f32_16x16x32_bf16 v[108:111], v[128:131], v[168:171], v[108:111]
	v_mfma_f32_16x16x32_bf16 v[104:107], v[136:139], v[168:171], v[104:107]
	v_mfma_f32_16x16x32_bf16 v[92:95], v[128:131], v[192:195], v[92:95]
	v_mfma_f32_16x16x32_bf16 v[88:91], v[136:139], v[192:195], v[88:91]
	v_mfma_f32_16x16x32_bf16 v[76:79], v[128:131], v[200:203], v[76:79]
	v_mfma_f32_16x16x32_bf16 v[72:75], v[136:139], v[200:203], v[72:75]
	v_mfma_f32_16x16x32_bf16 v[124:127], v[132:135], v[164:167], v[124:127]
	v_mfma_f32_16x16x32_bf16 v[120:123], v[140:143], v[164:167], v[120:123]
	v_mfma_f32_16x16x32_bf16 v[108:111], v[132:135], v[172:175], v[108:111]
	v_mfma_f32_16x16x32_bf16 v[104:107], v[140:143], v[172:175], v[104:107]
	v_mfma_f32_16x16x32_bf16 v[92:95], v[132:135], v[196:199], v[92:95]
	v_mfma_f32_16x16x32_bf16 v[88:91], v[140:143], v[196:199], v[88:91]
	v_mfma_f32_16x16x32_bf16 v[76:79], v[132:135], v[212:215], v[76:79]
	v_mfma_f32_16x16x32_bf16 v[72:75], v[140:143], v[212:215], v[72:75]
	v_mfma_f32_16x16x32_bf16 v[116:119], v[144:147], v[160:163], v[116:119]
	v_mfma_f32_16x16x32_bf16 v[112:115], v[152:155], v[160:163], v[112:115]
	v_mfma_f32_16x16x32_bf16 v[100:103], v[144:147], v[168:171], v[100:103]
	v_mfma_f32_16x16x32_bf16 v[96:99], v[152:155], v[168:171], v[96:99]
	v_mfma_f32_16x16x32_bf16 v[84:87], v[144:147], v[192:195], v[84:87]
	v_mfma_f32_16x16x32_bf16 v[80:83], v[152:155], v[192:195], v[80:83]
	v_mfma_f32_16x16x32_bf16 v[68:71], v[144:147], v[200:203], v[68:71]
	v_mfma_f32_16x16x32_bf16 v[64:67], v[152:155], v[200:203], v[64:67]
	v_mfma_f32_16x16x32_bf16 v[116:119], v[148:151], v[164:167], v[116:119]
	v_mfma_f32_16x16x32_bf16 v[112:115], v[156:159], v[164:167], v[112:115]
	v_mfma_f32_16x16x32_bf16 v[100:103], v[148:151], v[172:175], v[100:103]
	v_mfma_f32_16x16x32_bf16 v[96:99], v[156:159], v[172:175], v[96:99]
	v_mfma_f32_16x16x32_bf16 v[84:87], v[148:151], v[196:199], v[84:87]
	v_mfma_f32_16x16x32_bf16 v[80:83], v[156:159], v[196:199], v[80:83]
	v_mfma_f32_16x16x32_bf16 v[68:71], v[148:151], v[212:215], v[68:71]
	v_mfma_f32_16x16x32_bf16 v[64:67], v[156:159], v[212:215], v[64:67]
	s_setprio 0
	s_barrier
	s_add_i32 s30, s58, s3
	s_mov_b32 m0, s30
	ds_read_b128 v[160:163], v209 offset:49152
	ds_read_b128 v[164:167], v209 offset:50176
	ds_read_b128 v[168:171], v209 offset:51200
	ds_read_b128 v[172:175], v209 offset:52224
	global_load_lds_dwordx4 v178, s[98:99]
	s_add_i32 m0, s30, 0x2000
	s_add_u32 s28, s28, 0x100080
	s_addc_u32 s29, s29, 0
	s_add_i32 s30, s59, s3
	global_load_lds_dwordx4 v182, s[98:99]
	s_mov_b32 m0, s30
	ds_read_b128 v[212:215], v209 offset:56320
	global_load_lds_dwordx4 v178, s[28:29]
	s_add_i32 m0, s30, 0x2000
	ds_read_b128 v[200:203], v209 offset:55296
	global_load_lds_dwordx4 v182, s[28:29]
	s_mov_b32 m0, s38
	ds_read_b128 v[196:199], v209 offset:54272
	global_load_lds_dwordx4 v176, s[100:101]
	s_mov_b32 m0, s39
	ds_read_b128 v[192:195], v209 offset:53248
	global_load_lds_dwordx4 v180, s[100:101]
	s_waitcnt vmcnt(8)
	s_waitcnt lgkmcnt(0)
	s_barrier
	s_setprio 1
	s_waitcnt lgkmcnt(0)
	v_mfma_f32_16x16x32_bf16 v[60:63], v[128:131], v[160:163], v[60:63]
	v_mfma_f32_16x16x32_bf16 v[56:59], v[136:139], v[160:163], v[56:59]
	v_mfma_f32_16x16x32_bf16 v[44:47], v[128:131], v[168:171], v[44:47]
	v_mfma_f32_16x16x32_bf16 v[40:43], v[136:139], v[168:171], v[40:43]
	v_mfma_f32_16x16x32_bf16 v[28:31], v[128:131], v[192:195], v[28:31]
	v_mfma_f32_16x16x32_bf16 v[24:27], v[136:139], v[192:195], v[24:27]
	v_mfma_f32_16x16x32_bf16 v[12:15], v[128:131], v[200:203], v[12:15]
	v_mfma_f32_16x16x32_bf16 v[8:11], v[136:139], v[200:203], v[8:11]
	v_mfma_f32_16x16x32_bf16 v[60:63], v[132:135], v[164:167], v[60:63]
	v_mfma_f32_16x16x32_bf16 v[56:59], v[140:143], v[164:167], v[56:59]
	v_mfma_f32_16x16x32_bf16 v[44:47], v[132:135], v[172:175], v[44:47]
	v_mfma_f32_16x16x32_bf16 v[40:43], v[140:143], v[172:175], v[40:43]
	v_mfma_f32_16x16x32_bf16 v[28:31], v[132:135], v[196:199], v[28:31]
	v_mfma_f32_16x16x32_bf16 v[24:27], v[140:143], v[196:199], v[24:27]
	v_mfma_f32_16x16x32_bf16 v[12:15], v[132:135], v[212:215], v[12:15]
	v_mfma_f32_16x16x32_bf16 v[8:11], v[140:143], v[212:215], v[8:11]
	v_mfma_f32_16x16x32_bf16 v[52:55], v[144:147], v[160:163], v[52:55]
	v_mfma_f32_16x16x32_bf16 v[48:51], v[152:155], v[160:163], v[48:51]
	v_mfma_f32_16x16x32_bf16 v[36:39], v[144:147], v[168:171], v[36:39]
	v_mfma_f32_16x16x32_bf16 v[32:35], v[152:155], v[168:171], v[32:35]
	v_mfma_f32_16x16x32_bf16 v[20:23], v[144:147], v[192:195], v[20:23]
	v_mfma_f32_16x16x32_bf16 v[16:19], v[152:155], v[192:195], v[16:19]
	v_mfma_f32_16x16x32_bf16 v[4:7], v[144:147], v[200:203], v[4:7]
	v_mfma_f32_16x16x32_bf16 v[0:3], v[152:155], v[200:203], v[0:3]
	v_mfma_f32_16x16x32_bf16 v[52:55], v[148:151], v[164:167], v[52:55]
	v_mfma_f32_16x16x32_bf16 v[48:51], v[156:159], v[164:167], v[48:51]
	v_mfma_f32_16x16x32_bf16 v[36:39], v[148:151], v[172:175], v[36:39]
	v_mfma_f32_16x16x32_bf16 v[32:35], v[156:159], v[172:175], v[32:35]
	v_mfma_f32_16x16x32_bf16 v[20:23], v[148:151], v[196:199], v[20:23]
	v_mfma_f32_16x16x32_bf16 v[16:19], v[156:159], v[196:199], v[16:19]
	v_mfma_f32_16x16x32_bf16 v[4:7], v[148:151], v[212:215], v[4:7]
	v_mfma_f32_16x16x32_bf16 v[0:3], v[156:159], v[212:215], v[0:3]
	s_setprio 0
	s_barrier
	s_add_i32 s55, s55, 2
	s_add_u32 s26, s26, 0x100
	s_addc_u32 s27, s27, 0
	s_add_u32 s53, s53, 0x100
	s_addc_u32 s54, s54, 0
	s_cmp_gt_u32 s55, 61
	s_cbranch_scc0 .LBB0_431
	s_and_b64 vcc, exec, s[10:11]
	s_cbranch_vccz .LBB0_434
	s_barrier

.LBB0_528:
	ds_read_b128 v[134:137], v200
	ds_read_b128 v[138:141], v200 offset:1024
	ds_read_b128 v[162:165], v200 offset:2048
	ds_read_b128 v[166:169], v200 offset:3072
	ds_read_b128 v[170:173], v201
	ds_read_b128 v[174:177], v201 offset:1024
	ds_read_b128 v[178:181], v201 offset:2048
	ds_read_b128 v[206:209], v201 offset:3072
	s_add_u32 s62, s20, 0xfff00080
	s_addc_u32 s63, s21, -1
	s_cmp_eq_u32 s83, 60
	s_cselect_b32 s79, s47, s63
	s_cselect_b32 s78, s57, s62
	s_cselect_b32 s63, s41, s82
	s_cselect_b32 s62, s59, s81
	s_add_u32 s98, s62, s30
	s_addc_u32 s99, s63, s31
	s_add_u32 s100, s78, s30
	s_addc_u32 s101, s79, s31
	s_add_i32 m0, s39, 0xc000
	ds_read_b128 v[210:213], v202
	ds_read_b128 v[214:217], v202 offset:1024
	ds_read_b128 v[218:221], v202 offset:2048
	ds_read_b128 v[222:225], v202 offset:3072
	ds_read_b128 v[226:229], v202 offset:4096
	ds_read_b128 v[230:233], v202 offset:5120
	ds_read_b128 v[234:237], v202 offset:6144
	global_load_lds_dwordx4 v154, s[20:21]
	s_add_i32 m0, s39, 0xe000
	ds_read_b128 v[238:241], v202 offset:7168
	global_load_lds_dwordx4 v156, s[20:21]
	s_waitcnt vmcnt(8)
	s_waitcnt lgkmcnt(0)
	s_barrier
	s_setprio 1
	s_waitcnt lgkmcnt(0)
	v_mfma_f32_16x16x32_bf16 v[130:133], v[210:213], v[134:137], v[130:133]
	v_mfma_f32_16x16x32_bf16 v[126:129], v[210:213], v[162:165], v[126:129]
	v_mfma_f32_16x16x32_bf16 v[122:125], v[218:221], v[134:137], v[122:125]
	v_mfma_f32_16x16x32_bf16 v[118:121], v[218:221], v[162:165], v[118:121]
	v_mfma_f32_16x16x32_bf16 v[114:117], v[226:229], v[134:137], v[114:117]
	v_mfma_f32_16x16x32_bf16 v[110:113], v[226:229], v[162:165], v[110:113]
	v_mfma_f32_16x16x32_bf16 v[106:109], v[234:237], v[134:137], v[106:109]
	v_mfma_f32_16x16x32_bf16 v[102:105], v[234:237], v[162:165], v[102:105]
	v_mfma_f32_16x16x32_bf16 v[130:133], v[214:217], v[138:141], v[130:133]
	v_mfma_f32_16x16x32_bf16 v[126:129], v[214:217], v[166:169], v[126:129]
	v_mfma_f32_16x16x32_bf16 v[122:125], v[222:225], v[138:141], v[122:125]
	v_mfma_f32_16x16x32_bf16 v[118:121], v[222:225], v[166:169], v[118:121]
	v_mfma_f32_16x16x32_bf16 v[114:117], v[230:233], v[138:141], v[114:117]
	v_mfma_f32_16x16x32_bf16 v[110:113], v[230:233], v[166:169], v[110:113]
	v_mfma_f32_16x16x32_bf16 v[106:109], v[238:241], v[138:141], v[106:109]
	v_mfma_f32_16x16x32_bf16 v[102:105], v[238:241], v[166:169], v[102:105]
	v_mfma_f32_16x16x32_bf16 v[64:67], v[170:173], v[210:213], v[64:67]
	v_mfma_f32_16x16x32_bf16 v[60:63], v[178:181], v[210:213], v[60:63]
	v_mfma_f32_16x16x32_bf16 v[56:59], v[170:173], v[218:221], v[56:59]
	v_mfma_f32_16x16x32_bf16 v[52:55], v[178:181], v[218:221], v[52:55]
	v_mfma_f32_16x16x32_bf16 v[48:51], v[170:173], v[226:229], v[48:51]
	v_mfma_f32_16x16x32_bf16 v[44:47], v[178:181], v[226:229], v[44:47]
	v_mfma_f32_16x16x32_bf16 v[40:43], v[170:173], v[234:237], v[40:43]
	v_mfma_f32_16x16x32_bf16 v[36:39], v[178:181], v[234:237], v[36:39]
	v_mfma_f32_16x16x32_bf16 v[64:67], v[174:177], v[214:217], v[64:67]
	v_mfma_f32_16x16x32_bf16 v[60:63], v[206:209], v[214:217], v[60:63]
	v_mfma_f32_16x16x32_bf16 v[56:59], v[174:177], v[222:225], v[56:59]
	v_mfma_f32_16x16x32_bf16 v[52:55], v[206:209], v[222:225], v[52:55]
	v_mfma_f32_16x16x32_bf16 v[48:51], v[174:177], v[230:233], v[48:51]
	v_mfma_f32_16x16x32_bf16 v[44:47], v[206:209], v[230:233], v[44:47]
	v_mfma_f32_16x16x32_bf16 v[40:43], v[174:177], v[238:241], v[40:43]
	v_mfma_f32_16x16x32_bf16 v[36:39], v[206:209], v[238:241], v[36:39]
	s_setprio 0
	s_barrier
	s_add_i32 s84, s75, s3
	s_mov_b32 m0, s84
	ds_read_b128 v[210:213], v202 offset:16384
	ds_read_b128 v[214:217], v202 offset:17408
	ds_read_b128 v[218:221], v202 offset:18432
	ds_read_b128 v[222:225], v202 offset:19456
	global_load_lds_dwordx4 v144, s[62:63]
	s_add_i32 m0, s84, 0x2000
	s_add_u32 s84, s62, 0x100000
	s_addc_u32 s85, s63, 0
	s_add_i32 s86, s80, s3
	global_load_lds_dwordx4 v148, s[62:63]
	s_mov_b32 m0, s86
	ds_read_b128 v[238:241], v202 offset:23552
	global_load_lds_dwordx4 v144, s[84:85]
	s_add_i32 m0, s86, 0x2000
	ds_read_b128 v[234:237], v202 offset:22528
	global_load_lds_dwordx4 v148, s[84:85]
	s_mov_b32 m0, s39
	ds_read_b128 v[230:233], v202 offset:21504
	global_load_lds_dwordx4 v142, s[78:79]
	s_mov_b32 m0, s54
	ds_read_b128 v[226:229], v202 offset:20480
	global_load_lds_dwordx4 v146, s[78:79]
	s_waitcnt vmcnt(8)
	s_waitcnt lgkmcnt(0)
	s_barrier
	s_setprio 1
	s_waitcnt lgkmcnt(0)
	v_mfma_f32_16x16x32_bf16 v[98:101], v[210:213], v[134:137], v[98:101]
	v_mfma_f32_16x16x32_bf16 v[94:97], v[210:213], v[162:165], v[94:97]
	v_mfma_f32_16x16x32_bf16 v[90:93], v[218:221], v[134:137], v[90:93]
	v_mfma_f32_16x16x32_bf16 v[86:89], v[218:221], v[162:165], v[86:89]
	v_mfma_f32_16x16x32_bf16 v[82:85], v[226:229], v[134:137], v[82:85]
	v_mfma_f32_16x16x32_bf16 v[68:71], v[226:229], v[162:165], v[68:71]
	v_mfma_f32_16x16x32_bf16 v[72:75], v[234:237], v[134:137], v[74:77]
	v_mfma_f32_16x16x32_bf16 v[76:79], v[234:237], v[162:165], v[78:81]
	v_mfma_f32_16x16x32_bf16 v[98:101], v[214:217], v[138:141], v[98:101]
	v_mfma_f32_16x16x32_bf16 v[94:97], v[214:217], v[166:169], v[94:97]
	v_mfma_f32_16x16x32_bf16 v[90:93], v[222:225], v[138:141], v[90:93]
	v_mfma_f32_16x16x32_bf16 v[86:89], v[222:225], v[166:169], v[86:89]
	v_mfma_f32_16x16x32_bf16 v[82:85], v[230:233], v[138:141], v[82:85]
	v_mfma_f32_16x16x32_bf16 v[68:71], v[230:233], v[166:169], v[68:71]
	v_mfma_f32_16x16x32_bf16 v[72:75], v[238:241], v[138:141], v[72:75]
	v_mfma_f32_16x16x32_bf16 v[78:81], v[238:241], v[166:169], v[76:79]
	v_mfma_f32_16x16x32_bf16 v[32:35], v[170:173], v[210:213], v[32:35]
	v_mfma_f32_16x16x32_bf16 v[28:31], v[178:181], v[210:213], v[28:31]
	v_mfma_f32_16x16x32_bf16 v[24:27], v[170:173], v[218:221], v[24:27]
	v_mfma_f32_16x16x32_bf16 v[20:23], v[178:181], v[218:221], v[20:23]
	v_mfma_f32_16x16x32_bf16 v[16:19], v[170:173], v[226:229], v[16:19]
	v_mfma_f32_16x16x32_bf16 v[12:15], v[178:181], v[226:229], v[12:15]
	v_mfma_f32_16x16x32_bf16 v[2:5], v[170:173], v[234:237], v[4:7]
	v_mfma_f32_16x16x32_bf16 v[6:9], v[178:181], v[234:237], v[8:11]
	v_mfma_f32_16x16x32_bf16 v[32:35], v[174:177], v[214:217], v[32:35]
	v_mfma_f32_16x16x32_bf16 v[28:31], v[206:209], v[214:217], v[28:31]
	v_mfma_f32_16x16x32_bf16 v[24:27], v[174:177], v[222:225], v[24:27]
	v_mfma_f32_16x16x32_bf16 v[20:23], v[206:209], v[222:225], v[20:23]
	v_mfma_f32_16x16x32_bf16 v[16:19], v[174:177], v[230:233], v[16:19]
	v_mfma_f32_16x16x32_bf16 v[12:15], v[206:209], v[230:233], v[12:15]
	v_mfma_f32_16x16x32_bf16 v[2:5], v[174:177], v[238:241], v[2:5]
	v_mfma_f32_16x16x32_bf16 v[8:11], v[206:209], v[238:241], v[6:9]
	s_setprio 0
	s_barrier
	s_add_i32 s84, 0, 0x18000
	v_add_u32_e32 v1, s84, v183
	s_add_i32 s85, 0, 0x1c000
	ds_read_b128 v[134:137], v1
	ds_read_b128 v[138:141], v1 offset:1024
	ds_read_b128 v[162:165], v1 offset:2048
	ds_read_b128 v[166:169], v1 offset:3072
	v_add_u32_e32 v1, s85, v183
	ds_read_b128 v[170:173], v1
	ds_read_b128 v[174:177], v1 offset:1024
	ds_read_b128 v[178:181], v1 offset:2048
	ds_read_b128 v[206:209], v1 offset:3072
	s_add_u32 s78, s78, 0x100000
	s_addc_u32 s79, s79, 0
	s_mov_b32 m0, s55
	ds_read_b128 v[210:213], v202 offset:32768
	ds_read_b128 v[214:217], v202 offset:33792
	ds_read_b128 v[218:221], v202 offset:34816
	ds_read_b128 v[222:225], v202 offset:35840
	ds_read_b128 v[226:229], v202 offset:36864
	ds_read_b128 v[230:233], v202 offset:37888
	ds_read_b128 v[234:237], v202 offset:38912
	global_load_lds_dwordx4 v142, s[78:79]
	s_mov_b32 m0, s68
	ds_read_b128 v[238:241], v202 offset:39936
	global_load_lds_dwordx4 v146, s[78:79]
	s_waitcnt vmcnt(8)
	s_waitcnt lgkmcnt(0)
	s_barrier
	s_setprio 1
	s_waitcnt lgkmcnt(0)
	v_mfma_f32_16x16x32_bf16 v[130:133], v[210:213], v[134:137], v[130:133]
	v_mfma_f32_16x16x32_bf16 v[126:129], v[210:213], v[162:165], v[126:129]
	v_mfma_f32_16x16x32_bf16 v[122:125], v[218:221], v[134:137], v[122:125]
	v_mfma_f32_16x16x32_bf16 v[118:121], v[218:221], v[162:165], v[118:121]
	v_mfma_f32_16x16x32_bf16 v[114:117], v[226:229], v[134:137], v[114:117]
	v_mfma_f32_16x16x32_bf16 v[110:113], v[226:229], v[162:165], v[110:113]
	v_mfma_f32_16x16x32_bf16 v[106:109], v[234:237], v[134:137], v[106:109]
	v_mfma_f32_16x16x32_bf16 v[102:105], v[234:237], v[162:165], v[102:105]
	v_mfma_f32_16x16x32_bf16 v[130:133], v[214:217], v[138:141], v[130:133]
	v_mfma_f32_16x16x32_bf16 v[126:129], v[214:217], v[166:169], v[126:129]
	v_mfma_f32_16x16x32_bf16 v[122:125], v[222:225], v[138:141], v[122:125]
	v_mfma_f32_16x16x32_bf16 v[118:121], v[222:225], v[166:169], v[118:121]
	v_mfma_f32_16x16x32_bf16 v[114:117], v[230:233], v[138:141], v[114:117]
	v_mfma_f32_16x16x32_bf16 v[110:113], v[230:233], v[166:169], v[110:113]
	v_mfma_f32_16x16x32_bf16 v[106:109], v[238:241], v[138:141], v[106:109]
	v_mfma_f32_16x16x32_bf16 v[102:105], v[238:241], v[166:169], v[102:105]
	v_mfma_f32_16x16x32_bf16 v[64:67], v[170:173], v[210:213], v[64:67]
	v_mfma_f32_16x16x32_bf16 v[60:63], v[178:181], v[210:213], v[60:63]
	v_mfma_f32_16x16x32_bf16 v[56:59], v[170:173], v[218:221], v[56:59]
	v_mfma_f32_16x16x32_bf16 v[52:55], v[178:181], v[218:221], v[52:55]
	v_mfma_f32_16x16x32_bf16 v[48:51], v[170:173], v[226:229], v[48:51]
	v_mfma_f32_16x16x32_bf16 v[44:47], v[178:181], v[226:229], v[44:47]
	v_mfma_f32_16x16x32_bf16 v[40:43], v[170:173], v[234:237], v[40:43]
	v_mfma_f32_16x16x32_bf16 v[36:39], v[178:181], v[234:237], v[36:39]
	v_mfma_f32_16x16x32_bf16 v[64:67], v[174:177], v[214:217], v[64:67]
	v_mfma_f32_16x16x32_bf16 v[60:63], v[206:209], v[214:217], v[60:63]
	v_mfma_f32_16x16x32_bf16 v[56:59], v[174:177], v[222:225], v[56:59]
	v_mfma_f32_16x16x32_bf16 v[52:55], v[206:209], v[222:225], v[52:55]
	v_mfma_f32_16x16x32_bf16 v[48:51], v[174:177], v[230:233], v[48:51]
	v_mfma_f32_16x16x32_bf16 v[44:47], v[206:209], v[230:233], v[44:47]
	v_mfma_f32_16x16x32_bf16 v[40:43], v[174:177], v[238:241], v[40:43]
	v_mfma_f32_16x16x32_bf16 v[36:39], v[206:209], v[238:241], v[36:39]
	s_setprio 0
	s_barrier
	s_add_i32 s78, s84, s3
	s_mov_b32 m0, s78
	ds_read_b128 v[210:213], v202 offset:49152
	ds_read_b128 v[214:217], v202 offset:50176
	ds_read_b128 v[218:221], v202 offset:51200
	ds_read_b128 v[222:225], v202 offset:52224
	global_load_lds_dwordx4 v144, s[98:99]
	s_add_i32 m0, s78, 0x2000
	s_add_u32 s62, s62, 0x100080
	s_addc_u32 s63, s63, 0
	s_add_i32 s78, s85, s3
	global_load_lds_dwordx4 v148, s[98:99]
	s_mov_b32 m0, s78
	ds_read_b128 v[238:241], v202 offset:56320
	global_load_lds_dwordx4 v144, s[62:63]
	s_add_i32 m0, s78, 0x2000
	ds_read_b128 v[234:237], v202 offset:55296
	global_load_lds_dwordx4 v148, s[62:63]
	s_mov_b32 m0, s71
	ds_read_b128 v[230:233], v202 offset:54272
	global_load_lds_dwordx4 v142, s[100:101]
	s_mov_b32 m0, s72
	ds_read_b128 v[226:229], v202 offset:53248
	global_load_lds_dwordx4 v146, s[100:101]
	s_waitcnt vmcnt(8)
	s_waitcnt lgkmcnt(0)
	s_barrier
	s_setprio 1
	s_waitcnt lgkmcnt(0)
	v_mfma_f32_16x16x32_bf16 v[98:101], v[210:213], v[134:137], v[98:101]
	v_mfma_f32_16x16x32_bf16 v[94:97], v[210:213], v[162:165], v[94:97]
	v_mfma_f32_16x16x32_bf16 v[90:93], v[218:221], v[134:137], v[90:93]
	v_mfma_f32_16x16x32_bf16 v[86:89], v[218:221], v[162:165], v[86:89]
	v_mfma_f32_16x16x32_bf16 v[82:85], v[226:229], v[134:137], v[82:85]
	v_mfma_f32_16x16x32_bf16 v[68:71], v[226:229], v[162:165], v[68:71]
	v_mfma_f32_16x16x32_bf16 v[72:75], v[234:237], v[134:137], v[72:75]
	v_mfma_f32_16x16x32_bf16 v[78:81], v[234:237], v[162:165], v[78:81]
	v_mfma_f32_16x16x32_bf16 v[98:101], v[214:217], v[138:141], v[98:101]
	v_mfma_f32_16x16x32_bf16 v[94:97], v[214:217], v[166:169], v[94:97]
	v_mfma_f32_16x16x32_bf16 v[90:93], v[222:225], v[138:141], v[90:93]
	v_mfma_f32_16x16x32_bf16 v[86:89], v[222:225], v[166:169], v[86:89]
	v_mfma_f32_16x16x32_bf16 v[82:85], v[230:233], v[138:141], v[82:85]
	v_mfma_f32_16x16x32_bf16 v[68:71], v[230:233], v[166:169], v[68:71]
	v_mfma_f32_16x16x32_bf16 v[74:77], v[238:241], v[138:141], v[72:75]
	v_mfma_f32_16x16x32_bf16 v[78:81], v[238:241], v[166:169], v[78:81]
	v_mfma_f32_16x16x32_bf16 v[32:35], v[170:173], v[210:213], v[32:35]
	v_mfma_f32_16x16x32_bf16 v[28:31], v[178:181], v[210:213], v[28:31]
	v_mfma_f32_16x16x32_bf16 v[24:27], v[170:173], v[218:221], v[24:27]
	v_mfma_f32_16x16x32_bf16 v[20:23], v[178:181], v[218:221], v[20:23]
	v_mfma_f32_16x16x32_bf16 v[16:19], v[170:173], v[226:229], v[16:19]
	v_mfma_f32_16x16x32_bf16 v[12:15], v[178:181], v[226:229], v[12:15]
	v_mfma_f32_16x16x32_bf16 v[2:5], v[170:173], v[234:237], v[2:5]
	v_mfma_f32_16x16x32_bf16 v[8:11], v[178:181], v[234:237], v[8:11]
	v_mfma_f32_16x16x32_bf16 v[32:35], v[174:177], v[214:217], v[32:35]
	v_mfma_f32_16x16x32_bf16 v[28:31], v[206:209], v[214:217], v[28:31]
	v_mfma_f32_16x16x32_bf16 v[24:27], v[174:177], v[222:225], v[24:27]
	v_mfma_f32_16x16x32_bf16 v[20:23], v[206:209], v[222:225], v[20:23]
	v_mfma_f32_16x16x32_bf16 v[16:19], v[174:177], v[230:233], v[16:19]
	v_mfma_f32_16x16x32_bf16 v[12:15], v[206:209], v[230:233], v[12:15]
	v_mfma_f32_16x16x32_bf16 v[4:7], v[174:177], v[238:241], v[2:5]
	v_mfma_f32_16x16x32_bf16 v[8:11], v[206:209], v[238:241], v[8:11]
	s_setprio 0
	s_barrier
	s_add_i32 s83, s83, 2
	s_add_u32 s20, s20, 0x100
	s_addc_u32 s21, s21, 0
	s_add_u32 s81, s81, 0x100
	s_addc_u32 s82, s82, 0
	s_cmp_gt_u32 s83, 61
	s_cbranch_scc0 .LBB0_528
	s_and_b64 vcc, exec, s[34:35]
	s_cbranch_vccz .LBB0_531
	s_barrier

.LBB0_815:
	ds_read_b128 v[56:59], v241
	ds_read_b128 v[60:63], v241 offset:1024
	ds_read_b128 v[64:67], v241 offset:2048
	ds_read_b128 v[68:71], v241 offset:3072
	ds_read_b128 v[144:147], v242
	ds_read_b128 v[148:151], v242 offset:1024
	ds_read_b128 v[152:155], v242 offset:2048
	ds_read_b128 v[156:159], v242 offset:3072
	s_add_u32 s50, s46, 0xffe00080
	s_addc_u32 s51, s47, -1
	s_cmpk_eq_i32 s77, 0x7c
	s_cselect_b32 s53, s29, s51
	s_cselect_b32 s52, s39, s50
	s_cselect_b32 s51, s31, s76
	s_cselect_b32 s50, s41, s75
	s_add_u32 s98, s50, s12
	s_addc_u32 s99, s51, s13
	s_add_u32 s100, s52, s12
	s_addc_u32 s101, s53, s13
	s_add_i32 m0, s55, 0xc000
	ds_read_b128 v[160:163], v243
	ds_read_b128 v[164:167], v243 offset:1024
	ds_read_b128 v[168:171], v243 offset:2048
	ds_read_b128 v[172:175], v243 offset:3072
	ds_read_b128 v[176:179], v243 offset:4096
	ds_read_b128 v[180:183], v243 offset:5120
	ds_read_b128 v[184:187], v243 offset:6144
	global_load_lds_dwordx4 v216, s[46:47]
	s_add_i32 m0, s55, 0xe000
	ds_read_b128 v[188:191], v243 offset:7168
	global_load_lds_dwordx4 v218, s[46:47]
	s_waitcnt vmcnt(8)
	s_waitcnt lgkmcnt(0)
	s_barrier
	s_setprio 1
	s_waitcnt lgkmcnt(0)
	v_mfma_f32_16x16x32_bf16 v[140:143], v[56:59], v[160:163], v[140:143]
	v_mfma_f32_16x16x32_bf16 v[136:139], v[64:67], v[160:163], v[136:139]
	v_mfma_f32_16x16x32_bf16 v[124:127], v[56:59], v[168:171], v[124:127]
	v_mfma_f32_16x16x32_bf16 v[120:123], v[64:67], v[168:171], v[120:123]
	v_mfma_f32_16x16x32_bf16 v[108:111], v[56:59], v[176:179], v[108:111]
	v_mfma_f32_16x16x32_bf16 v[104:107], v[64:67], v[176:179], v[104:107]
	v_mfma_f32_16x16x32_bf16 v[92:95], v[56:59], v[184:187], v[92:95]
	v_mfma_f32_16x16x32_bf16 v[88:91], v[64:67], v[184:187], v[88:91]
	v_mfma_f32_16x16x32_bf16 v[140:143], v[60:63], v[164:167], v[140:143]
	v_mfma_f32_16x16x32_bf16 v[136:139], v[68:71], v[164:167], v[136:139]
	v_mfma_f32_16x16x32_bf16 v[124:127], v[60:63], v[172:175], v[124:127]
	v_mfma_f32_16x16x32_bf16 v[120:123], v[68:71], v[172:175], v[120:123]
	v_mfma_f32_16x16x32_bf16 v[108:111], v[60:63], v[180:183], v[108:111]
	v_mfma_f32_16x16x32_bf16 v[104:107], v[68:71], v[180:183], v[104:107]
	v_mfma_f32_16x16x32_bf16 v[92:95], v[60:63], v[188:191], v[92:95]
	v_mfma_f32_16x16x32_bf16 v[88:91], v[68:71], v[188:191], v[88:91]
	v_mfma_f32_16x16x32_bf16 v[132:135], v[144:147], v[160:163], v[132:135]
	v_mfma_f32_16x16x32_bf16 v[128:131], v[152:155], v[160:163], v[128:131]
	v_mfma_f32_16x16x32_bf16 v[116:119], v[144:147], v[168:171], v[116:119]
	v_mfma_f32_16x16x32_bf16 v[112:115], v[152:155], v[168:171], v[112:115]
	v_mfma_f32_16x16x32_bf16 v[100:103], v[144:147], v[176:179], v[100:103]
	v_mfma_f32_16x16x32_bf16 v[96:99], v[152:155], v[176:179], v[96:99]
	v_mfma_f32_16x16x32_bf16 v[84:87], v[144:147], v[184:187], v[84:87]
	v_mfma_f32_16x16x32_bf16 v[80:83], v[152:155], v[184:187], v[80:83]
	v_mfma_f32_16x16x32_bf16 v[132:135], v[148:151], v[164:167], v[132:135]
	v_mfma_f32_16x16x32_bf16 v[128:131], v[156:159], v[164:167], v[128:131]
	v_mfma_f32_16x16x32_bf16 v[116:119], v[148:151], v[172:175], v[116:119]
	v_mfma_f32_16x16x32_bf16 v[112:115], v[156:159], v[172:175], v[112:115]
	v_mfma_f32_16x16x32_bf16 v[100:103], v[148:151], v[180:183], v[100:103]
	v_mfma_f32_16x16x32_bf16 v[96:99], v[156:159], v[180:183], v[96:99]
	v_mfma_f32_16x16x32_bf16 v[84:87], v[148:151], v[188:191], v[84:87]
	v_mfma_f32_16x16x32_bf16 v[80:83], v[156:159], v[188:191], v[80:83]
	s_setprio 0
	s_barrier
	s_add_i32 s78, s73, s54
	s_mov_b32 m0, s78
	ds_read_b128 v[160:163], v243 offset:16384
	ds_read_b128 v[164:167], v243 offset:17408
	ds_read_b128 v[168:171], v243 offset:18432
	ds_read_b128 v[172:175], v243 offset:19456
	global_load_lds_dwordx4 v210, s[50:51]
	s_add_i32 m0, s78, 0x2000
	s_add_u32 s78, s50, 0x200000
	s_addc_u32 s79, s51, 0
	s_add_i32 s80, s74, s54
	global_load_lds_dwordx4 v214, s[50:51]
	s_mov_b32 m0, s80
	ds_read_b128 v[188:191], v243 offset:23552
	global_load_lds_dwordx4 v210, s[78:79]
	s_add_i32 m0, s80, 0x2000
	ds_read_b128 v[184:187], v243 offset:22528
	global_load_lds_dwordx4 v214, s[78:79]
	s_mov_b32 m0, s55
	ds_read_b128 v[180:183], v243 offset:21504
	global_load_lds_dwordx4 v208, s[52:53]
	s_mov_b32 m0, s56
	ds_read_b128 v[176:179], v243 offset:20480
	global_load_lds_dwordx4 v212, s[52:53]
	s_waitcnt vmcnt(8)
	s_waitcnt lgkmcnt(0)
	s_barrier
	s_setprio 1
	s_waitcnt lgkmcnt(0)
	v_mfma_f32_16x16x32_bf16 v[76:79], v[56:59], v[160:163], v[76:79]
	v_mfma_f32_16x16x32_bf16 v[72:75], v[64:67], v[160:163], v[72:75]
	v_mfma_f32_16x16x32_bf16 v[44:47], v[56:59], v[168:171], v[44:47]
	v_mfma_f32_16x16x32_bf16 v[40:43], v[64:67], v[168:171], v[40:43]
	v_mfma_f32_16x16x32_bf16 v[28:31], v[56:59], v[176:179], v[28:31]
	v_mfma_f32_16x16x32_bf16 v[24:27], v[64:67], v[176:179], v[24:27]
	v_mfma_f32_16x16x32_bf16 v[12:15], v[56:59], v[184:187], v[12:15]
	v_mfma_f32_16x16x32_bf16 v[8:11], v[64:67], v[184:187], v[8:11]
	v_mfma_f32_16x16x32_bf16 v[76:79], v[60:63], v[164:167], v[76:79]
	v_mfma_f32_16x16x32_bf16 v[72:75], v[68:71], v[164:167], v[72:75]
	v_mfma_f32_16x16x32_bf16 v[44:47], v[60:63], v[172:175], v[44:47]
	v_mfma_f32_16x16x32_bf16 v[40:43], v[68:71], v[172:175], v[40:43]
	v_mfma_f32_16x16x32_bf16 v[28:31], v[60:63], v[180:183], v[28:31]
	v_mfma_f32_16x16x32_bf16 v[24:27], v[68:71], v[180:183], v[24:27]
	v_mfma_f32_16x16x32_bf16 v[12:15], v[60:63], v[188:191], v[12:15]
	v_mfma_f32_16x16x32_bf16 v[8:11], v[68:71], v[188:191], v[8:11]
	v_mfma_f32_16x16x32_bf16 v[52:55], v[144:147], v[160:163], v[52:55]
	v_mfma_f32_16x16x32_bf16 v[48:51], v[152:155], v[160:163], v[48:51]
	v_mfma_f32_16x16x32_bf16 v[36:39], v[144:147], v[168:171], v[36:39]
	v_mfma_f32_16x16x32_bf16 v[32:35], v[152:155], v[168:171], v[32:35]
	v_mfma_f32_16x16x32_bf16 v[20:23], v[144:147], v[176:179], v[20:23]
	v_mfma_f32_16x16x32_bf16 v[16:19], v[152:155], v[176:179], v[16:19]
	v_mfma_f32_16x16x32_bf16 v[4:7], v[144:147], v[184:187], v[4:7]
	v_mfma_f32_16x16x32_bf16 v[0:3], v[152:155], v[184:187], v[0:3]
	v_mfma_f32_16x16x32_bf16 v[52:55], v[148:151], v[164:167], v[52:55]
	v_mfma_f32_16x16x32_bf16 v[48:51], v[156:159], v[164:167], v[48:51]
	v_mfma_f32_16x16x32_bf16 v[36:39], v[148:151], v[172:175], v[36:39]
	v_mfma_f32_16x16x32_bf16 v[32:35], v[156:159], v[172:175], v[32:35]
	v_mfma_f32_16x16x32_bf16 v[20:23], v[148:151], v[180:183], v[20:23]
	v_mfma_f32_16x16x32_bf16 v[16:19], v[156:159], v[180:183], v[16:19]
	v_mfma_f32_16x16x32_bf16 v[4:7], v[148:151], v[188:191], v[4:7]
	v_mfma_f32_16x16x32_bf16 v[0:3], v[156:159], v[188:191], v[0:3]
	s_setprio 0
	s_barrier
	s_add_i32 s78, 0, 0x18000
	s_add_i32 s79, 0, 0x1c000
	v_add_u32_e32 v68, s78, v239
	v_add_u32_e32 v156, s79, v239
	ds_read_b128 v[56:59], v68
	ds_read_b128 v[60:63], v68 offset:1024
	ds_read_b128 v[64:67], v68 offset:2048
	ds_read_b128 v[68:71], v68 offset:3072
	ds_read_b128 v[144:147], v156
	ds_read_b128 v[148:151], v156 offset:1024
	ds_read_b128 v[152:155], v156 offset:2048
	ds_read_b128 v[156:159], v156 offset:3072
	s_add_u32 s52, s52, 0x200000
	s_addc_u32 s53, s53, 0
	s_mov_b32 m0, s57
	ds_read_b128 v[160:163], v243 offset:32768
	ds_read_b128 v[164:167], v243 offset:33792
	ds_read_b128 v[168:171], v243 offset:34816
	ds_read_b128 v[172:175], v243 offset:35840
	ds_read_b128 v[176:179], v243 offset:36864
	ds_read_b128 v[180:183], v243 offset:37888
	ds_read_b128 v[184:187], v243 offset:38912
	global_load_lds_dwordx4 v208, s[52:53]
	s_mov_b32 m0, s58
	ds_read_b128 v[188:191], v243 offset:39936
	global_load_lds_dwordx4 v212, s[52:53]
	s_waitcnt vmcnt(8)
	s_waitcnt lgkmcnt(0)
	s_barrier
	s_setprio 1
	s_waitcnt lgkmcnt(0)
	v_mfma_f32_16x16x32_bf16 v[140:143], v[56:59], v[160:163], v[140:143]
	v_mfma_f32_16x16x32_bf16 v[136:139], v[64:67], v[160:163], v[136:139]
	v_mfma_f32_16x16x32_bf16 v[124:127], v[56:59], v[168:171], v[124:127]
	v_mfma_f32_16x16x32_bf16 v[120:123], v[64:67], v[168:171], v[120:123]
	v_mfma_f32_16x16x32_bf16 v[108:111], v[56:59], v[176:179], v[108:111]
	v_mfma_f32_16x16x32_bf16 v[104:107], v[64:67], v[176:179], v[104:107]
	v_mfma_f32_16x16x32_bf16 v[92:95], v[56:59], v[184:187], v[92:95]
	v_mfma_f32_16x16x32_bf16 v[88:91], v[64:67], v[184:187], v[88:91]
	v_mfma_f32_16x16x32_bf16 v[140:143], v[60:63], v[164:167], v[140:143]
	v_mfma_f32_16x16x32_bf16 v[136:139], v[68:71], v[164:167], v[136:139]
	v_mfma_f32_16x16x32_bf16 v[124:127], v[60:63], v[172:175], v[124:127]
	v_mfma_f32_16x16x32_bf16 v[120:123], v[68:71], v[172:175], v[120:123]
	v_mfma_f32_16x16x32_bf16 v[108:111], v[60:63], v[180:183], v[108:111]
	v_mfma_f32_16x16x32_bf16 v[104:107], v[68:71], v[180:183], v[104:107]
	v_mfma_f32_16x16x32_bf16 v[92:95], v[60:63], v[188:191], v[92:95]
	v_mfma_f32_16x16x32_bf16 v[88:91], v[68:71], v[188:191], v[88:91]
	v_mfma_f32_16x16x32_bf16 v[132:135], v[144:147], v[160:163], v[132:135]
	v_mfma_f32_16x16x32_bf16 v[128:131], v[152:155], v[160:163], v[128:131]
	v_mfma_f32_16x16x32_bf16 v[116:119], v[144:147], v[168:171], v[116:119]
	v_mfma_f32_16x16x32_bf16 v[112:115], v[152:155], v[168:171], v[112:115]
	v_mfma_f32_16x16x32_bf16 v[100:103], v[144:147], v[176:179], v[100:103]
	v_mfma_f32_16x16x32_bf16 v[96:99], v[152:155], v[176:179], v[96:99]
	v_mfma_f32_16x16x32_bf16 v[84:87], v[144:147], v[184:187], v[84:87]
	v_mfma_f32_16x16x32_bf16 v[80:83], v[152:155], v[184:187], v[80:83]
	v_mfma_f32_16x16x32_bf16 v[132:135], v[148:151], v[164:167], v[132:135]
	v_mfma_f32_16x16x32_bf16 v[128:131], v[156:159], v[164:167], v[128:131]
	v_mfma_f32_16x16x32_bf16 v[116:119], v[148:151], v[172:175], v[116:119]
	v_mfma_f32_16x16x32_bf16 v[112:115], v[156:159], v[172:175], v[112:115]
	v_mfma_f32_16x16x32_bf16 v[100:103], v[148:151], v[180:183], v[100:103]
	v_mfma_f32_16x16x32_bf16 v[96:99], v[156:159], v[180:183], v[96:99]
	v_mfma_f32_16x16x32_bf16 v[84:87], v[148:151], v[188:191], v[84:87]
	v_mfma_f32_16x16x32_bf16 v[80:83], v[156:159], v[188:191], v[80:83]
	s_setprio 0
	s_barrier
	s_add_i32 s52, s78, s54
	s_mov_b32 m0, s52
	ds_read_b128 v[160:163], v243 offset:49152
	ds_read_b128 v[164:167], v243 offset:50176
	ds_read_b128 v[168:171], v243 offset:51200
	ds_read_b128 v[172:175], v243 offset:52224
	global_load_lds_dwordx4 v210, s[98:99]
	s_add_i32 m0, s52, 0x2000
	s_add_u32 s50, s50, 0x200080
	s_addc_u32 s51, s51, 0
	s_add_i32 s52, s79, s54
	global_load_lds_dwordx4 v214, s[98:99]
	s_mov_b32 m0, s52
	ds_read_b128 v[188:191], v243 offset:56320
	global_load_lds_dwordx4 v210, s[50:51]
	s_add_i32 m0, s52, 0x2000
	ds_read_b128 v[184:187], v243 offset:55296
	global_load_lds_dwordx4 v214, s[50:51]
	s_mov_b32 m0, s63
	ds_read_b128 v[180:183], v243 offset:54272
	global_load_lds_dwordx4 v208, s[100:101]
	s_mov_b32 m0, s68
	ds_read_b128 v[176:179], v243 offset:53248
	global_load_lds_dwordx4 v212, s[100:101]
	s_waitcnt vmcnt(8)
	s_waitcnt lgkmcnt(0)
	s_barrier
	s_setprio 1
	s_waitcnt lgkmcnt(0)
	v_mfma_f32_16x16x32_bf16 v[76:79], v[56:59], v[160:163], v[76:79]
	v_mfma_f32_16x16x32_bf16 v[72:75], v[64:67], v[160:163], v[72:75]
	v_mfma_f32_16x16x32_bf16 v[44:47], v[56:59], v[168:171], v[44:47]
	v_mfma_f32_16x16x32_bf16 v[40:43], v[64:67], v[168:171], v[40:43]
	v_mfma_f32_16x16x32_bf16 v[28:31], v[56:59], v[176:179], v[28:31]
	v_mfma_f32_16x16x32_bf16 v[24:27], v[64:67], v[176:179], v[24:27]
	v_mfma_f32_16x16x32_bf16 v[12:15], v[56:59], v[184:187], v[12:15]
	v_mfma_f32_16x16x32_bf16 v[8:11], v[64:67], v[184:187], v[8:11]
	v_mfma_f32_16x16x32_bf16 v[76:79], v[60:63], v[164:167], v[76:79]
	v_mfma_f32_16x16x32_bf16 v[72:75], v[68:71], v[164:167], v[72:75]
	v_mfma_f32_16x16x32_bf16 v[44:47], v[60:63], v[172:175], v[44:47]
	v_mfma_f32_16x16x32_bf16 v[40:43], v[68:71], v[172:175], v[40:43]
	v_mfma_f32_16x16x32_bf16 v[28:31], v[60:63], v[180:183], v[28:31]
	v_mfma_f32_16x16x32_bf16 v[24:27], v[68:71], v[180:183], v[24:27]
	v_mfma_f32_16x16x32_bf16 v[12:15], v[60:63], v[188:191], v[12:15]
	v_mfma_f32_16x16x32_bf16 v[8:11], v[68:71], v[188:191], v[8:11]
	v_mfma_f32_16x16x32_bf16 v[52:55], v[144:147], v[160:163], v[52:55]
	v_mfma_f32_16x16x32_bf16 v[48:51], v[152:155], v[160:163], v[48:51]
	v_mfma_f32_16x16x32_bf16 v[36:39], v[144:147], v[168:171], v[36:39]
	v_mfma_f32_16x16x32_bf16 v[32:35], v[152:155], v[168:171], v[32:35]
	v_mfma_f32_16x16x32_bf16 v[20:23], v[144:147], v[176:179], v[20:23]
	v_mfma_f32_16x16x32_bf16 v[16:19], v[152:155], v[176:179], v[16:19]
	v_mfma_f32_16x16x32_bf16 v[4:7], v[144:147], v[184:187], v[4:7]
	v_mfma_f32_16x16x32_bf16 v[0:3], v[152:155], v[184:187], v[0:3]
	v_mfma_f32_16x16x32_bf16 v[52:55], v[148:151], v[164:167], v[52:55]
	v_mfma_f32_16x16x32_bf16 v[48:51], v[156:159], v[164:167], v[48:51]
	v_mfma_f32_16x16x32_bf16 v[36:39], v[148:151], v[172:175], v[36:39]
	v_mfma_f32_16x16x32_bf16 v[32:35], v[156:159], v[172:175], v[32:35]
	v_mfma_f32_16x16x32_bf16 v[20:23], v[148:151], v[180:183], v[20:23]
	v_mfma_f32_16x16x32_bf16 v[16:19], v[156:159], v[180:183], v[16:19]
	v_mfma_f32_16x16x32_bf16 v[4:7], v[148:151], v[188:191], v[4:7]
	v_mfma_f32_16x16x32_bf16 v[0:3], v[156:159], v[188:191], v[0:3]
	s_setprio 0
	s_barrier
	s_add_i32 s77, s77, 2
	s_add_u32 s46, s46, 0x100
	s_addc_u32 s47, s47, 0
	s_add_u32 s75, s75, 0x100
	s_addc_u32 s76, s76, 0
	s_cmpk_gt_u32 s77, 0x7d
	s_cbranch_scc0 .LBB0_815
	s_and_b64 vcc, exec, s[14:15]
	s_cbranch_vccz .LBB0_818
	s_barrier
